# GEMM K-loops loop-edge edit: counter/pointer updates and exit compare moved in front of the closing barrier; first fragment-read group issued ahead of the scalar selects at the loop head
# baseline (speedup 1.0000x reference)
; #define PG8_STAGE(bufoff, gbase, voff) do { _Pragma("unroll") for (int _i = 0; _i < 2; ++_i) \
;         __builtin_amdgcn_global_load_lds((const unsigned*)((const char*)(gbase) + (voff)[_i]), (PG8_LAS unsigned*)(lds + (bufoff) + ldsw + _i * 8192), 16, 0, 0); } while (0)
; #define PG8_LDA(dst, b, h) do { _Pragma("unroll") for (int m = 0; m < 4; ++m) _Pragma("unroll") for (int k = 0; k < 2; ++k) dst[m][k] = *(const PG8_LAS bf16x8*)(lds + PG8_SA(b, h) + aoff + m * 2048 + k * 1024); } while (0)
; #define PG8_LDB(dst, b, h) do { _Pragma("unroll") for (int n = 0; n < 2; ++n) _Pragma("unroll") for (int k = 0; k < 2; ++k) dst[n][k] = *(const PG8_LAS bf16x8*)(lds + PG8_SB(b, h) + boff + n * 2048 + k * 1024); } while (0)
; #define PG8_MMA(ai, bj, At, Bt) do { __builtin_amdgcn_s_setprio(1); _Pragma("unroll") for (int m = 0; m < 4; ++m) _Pragma("unroll") for (int n = 0; n < 2; ++n) _Pragma("unroll") for (int k = 0; k < 2; ++k) \
;         acc[ai][bj][m][n] = __builtin_amdgcn_mfma_f32_16x16x32_bf16(Bt[n][k], At[m][k], acc[ai][bj][m][n], 0, 0, 0); __builtin_amdgcn_s_setprio(0); } while (0)
; #define PG8_WAIT_V(n) asm volatile("s_waitcnt vmcnt(" #n ")" ::: "memory")
; #define PG8_WAIT_L(n) asm volatile("s_waitcnt lgkmcnt(" #n ")" ::: "memory")
; template <class Epi, class Sched, bool ALIGN_EPI = false, bool SP2 = false>
; __device__ __forceinline__ void gemm_phase(PG8_LAS unsigned char* lds, const Gemm g, const Sched& S, const Epi& E) {
;     ...
;             const bool last = (t == nt - 2);
;             const char* a1 = cA + (size_t)(t + 1) * kstep;
;             const char* a2 = last ? nA : cA + (size_t)(t + 2) * kstep; const char* b2 = last ? nB : cB + (size_t)(t + 2) * kstep;
;             const char* a3 = a2 + kstep; const char* b3 = b2 + kstep;
;             if (last && has_next) S.a_ready(nxt);
;             if constexpr (SP2) {
;             PG8_LDB(B0, 0, 0); PG8_LDB(B1, 0, 1); PG8_SCHED; PG8_LDA(At, 0, 0); PG8_STAGE(PG8_SA(1, 1), a1 + hstep, voffA);
;             PG8_WAIT_V(8); PG8_WAIT_L(0); PG8_BAR; PG8_MMA(0, 0, At, B0); PG8_MMA(0, 1, At, B1); PG8_BAR; PG8_SCHED;
;             PG8_LDA(At, 0, 1); PG8_STAGE(PG8_SB(0, 0), b2, voffB); PG8_STAGE(PG8_SB(0, 1), b2 + hstep, voffB); PG8_STAGE(PG8_SA(0, 0), a2, voffA);
;             PG8_WAIT_V(8); PG8_WAIT_L(0); PG8_BAR; PG8_MMA(1, 0, At, B0); PG8_MMA(1, 1, At, B1); PG8_BAR; PG8_SCHED;
.LBB0_242:
	s_add_i32 s92, 0, 0x10000
	v_add_u32_e32 v144, s92, v146
	ds_read_b128 v[140:143], v144
	ds_read_b128 v[150:153], v144 offset:1024
	ds_read_b128 v[154:157], v144 offset:2048
	ds_read_b128 v[158:161], v144 offset:3072
	s_add_u32 s79, s86, 0xfffc0080
	s_addc_u32 s85, s87, -1
	s_cmp_eq_u32 s77, 12
	s_cselect_b32 s91, s49, s85
	s_cselect_b32 s90, s54, s79
	s_cselect_b32 s89, s55, s65
	s_cselect_b32 s88, s61, s64
	s_add_i32 s79, 0, 0x14000
	v_add_u32_e32 v144, s79, v146
	ds_read_b128 v[162:165], v144
	ds_read_b128 v[166:169], v144 offset:1024
	ds_read_b128 v[170:173], v144 offset:2048
	ds_read_b128 v[174:177], v144 offset:3072
	v_lshl_add_u64 v[212:213], s[86:87], 0, v[136:137]
	s_add_i32 m0, s7, 0xc000
	ds_read_b128 v[178:181], v149
	ds_read_b128 v[182:185], v149 offset:1024
	ds_read_b128 v[186:189], v149 offset:2048
	ds_read_b128 v[190:193], v149 offset:3072
	ds_read_b128 v[194:197], v149 offset:4096
	ds_read_b128 v[198:201], v149 offset:5120
	ds_read_b128 v[202:205], v149 offset:6144
	ds_read_b128 v[208:211], v149 offset:7168
	global_load_lds_dwordx4 v[212:213], off
	v_lshl_add_u64 v[212:213], s[86:87], 0, v[138:139]
	s_add_i32 m0, s7, 0xe000
	s_nop 0
	global_load_lds_dwordx4 v[212:213], off
	s_waitcnt vmcnt(8)
	s_waitcnt lgkmcnt(0)
	s_barrier
	s_setprio 1
	s_waitcnt lgkmcnt(0)
	v_mfma_f32_16x16x32_bf16 v[126:129], v[140:143], v[178:181], v[126:129]
	v_mfma_f32_16x16x32_bf16 v[122:125], v[154:157], v[178:181], v[122:125]
	v_mfma_f32_16x16x32_bf16 v[110:113], v[140:143], v[186:189], v[110:113]
	v_mfma_f32_16x16x32_bf16 v[106:109], v[154:157], v[186:189], v[106:109]
	v_mfma_f32_16x16x32_bf16 v[94:97], v[140:143], v[194:197], v[94:97]
	v_mfma_f32_16x16x32_bf16 v[90:93], v[154:157], v[194:197], v[90:93]
	v_mfma_f32_16x16x32_bf16 v[78:81], v[140:143], v[202:205], v[78:81]
	v_mfma_f32_16x16x32_bf16 v[74:77], v[154:157], v[202:205], v[74:77]
	v_mfma_f32_16x16x32_bf16 v[126:129], v[150:153], v[182:185], v[126:129]
	v_mfma_f32_16x16x32_bf16 v[122:125], v[158:161], v[182:185], v[122:125]
	v_mfma_f32_16x16x32_bf16 v[110:113], v[150:153], v[190:193], v[110:113]
	v_mfma_f32_16x16x32_bf16 v[106:109], v[158:161], v[190:193], v[106:109]
	v_mfma_f32_16x16x32_bf16 v[94:97], v[150:153], v[198:201], v[94:97]
	v_mfma_f32_16x16x32_bf16 v[90:93], v[158:161], v[198:201], v[90:93]
	v_mfma_f32_16x16x32_bf16 v[78:81], v[150:153], v[208:211], v[78:81]
	v_mfma_f32_16x16x32_bf16 v[74:77], v[158:161], v[208:211], v[74:77]
	s_setprio 0
	s_setprio 1
	v_mfma_f32_16x16x32_bf16 v[118:121], v[162:165], v[178:181], v[118:121]
	v_mfma_f32_16x16x32_bf16 v[114:117], v[170:173], v[178:181], v[114:117]
	v_mfma_f32_16x16x32_bf16 v[102:105], v[162:165], v[186:189], v[102:105]
	v_mfma_f32_16x16x32_bf16 v[98:101], v[170:173], v[186:189], v[98:101]
	v_mfma_f32_16x16x32_bf16 v[86:89], v[162:165], v[194:197], v[86:89]
	v_mfma_f32_16x16x32_bf16 v[82:85], v[170:173], v[194:197], v[82:85]
	v_mfma_f32_16x16x32_bf16 v[70:73], v[162:165], v[202:205], v[70:73]
	v_mfma_f32_16x16x32_bf16 v[66:69], v[170:173], v[202:205], v[66:69]
	v_mfma_f32_16x16x32_bf16 v[118:121], v[166:169], v[182:185], v[118:121]
	v_mfma_f32_16x16x32_bf16 v[114:117], v[174:177], v[182:185], v[114:117]
	v_mfma_f32_16x16x32_bf16 v[102:105], v[166:169], v[190:193], v[102:105]
	v_mfma_f32_16x16x32_bf16 v[98:101], v[174:177], v[190:193], v[98:101]
	v_mfma_f32_16x16x32_bf16 v[86:89], v[166:169], v[198:201], v[86:89]
	v_mfma_f32_16x16x32_bf16 v[82:85], v[174:177], v[198:201], v[82:85]
	v_mfma_f32_16x16x32_bf16 v[70:73], v[166:169], v[208:211], v[70:73]
	v_mfma_f32_16x16x32_bf16 v[66:69], v[174:177], v[208:211], v[66:69]
	s_setprio 0
	s_barrier
	s_add_i32 s85, s92, s14
	v_lshl_add_u64 v[212:213], s[88:89], 0, v[0:1]
	s_mov_b32 m0, s85
	ds_read_b128 v[178:181], v149 offset:16384
	ds_read_b128 v[182:185], v149 offset:17408
	ds_read_b128 v[186:189], v149 offset:18432
	ds_read_b128 v[190:193], v149 offset:19456
	ds_read_b128 v[194:197], v149 offset:20480
	ds_read_b128 v[198:201], v149 offset:21504
	ds_read_b128 v[202:205], v149 offset:22528
	ds_read_b128 v[208:211], v149 offset:23552
	global_load_lds_dwordx4 v[212:213], off
	s_add_i32 m0, s85, 0x2000
	s_add_u32 s92, s88, 0x40000
	v_lshl_add_u64 v[214:215], s[88:89], 0, v[134:135]
	s_addc_u32 s93, s89, 0
	s_add_i32 s79, s79, s14
	global_load_lds_dwordx4 v[214:215], off
	v_lshl_add_u64 v[216:217], s[92:93], 0, v[0:1]
	s_mov_b32 m0, s79
	v_lshl_add_u64 v[218:219], s[90:91], 0, v[132:133]
	global_load_lds_dwordx4 v[216:217], off
	v_lshl_add_u64 v[216:217], s[92:93], 0, v[134:135]
	s_add_i32 m0, s79, 0x2000
	s_nop 0
	global_load_lds_dwordx4 v[216:217], off
	v_lshl_add_u64 v[216:217], s[90:91], 0, v[130:131]
	s_mov_b32 m0, s7
	s_nop 0
	global_load_lds_dwordx4 v[216:217], off
	s_mov_b32 m0, s28
	s_nop 0
	global_load_lds_dwordx4 v[218:219], off
	s_waitcnt vmcnt(8)
	s_waitcnt lgkmcnt(0)
	s_barrier
; #define PG8_STAGE(bufoff, gbase, voff) do { _Pragma("unroll") for (int _i = 0; _i < 2; ++_i) \
;         __builtin_amdgcn_global_load_lds((const unsigned*)((const char*)(gbase) + (voff)[_i]), (PG8_LAS unsigned*)(lds + (bufoff) + ldsw + _i * 8192), 16, 0, 0); } while (0)
; #define PG8_LDA(dst, b, h) do { _Pragma("unroll") for (int m = 0; m < 4; ++m) _Pragma("unroll") for (int k = 0; k < 2; ++k) dst[m][k] = *(const PG8_LAS bf16x8*)(lds + PG8_SA(b, h) + aoff + m * 2048 + k * 1024); } while (0)
; #define PG8_LDB(dst, b, h) do { _Pragma("unroll") for (int n = 0; n < 2; ++n) _Pragma("unroll") for (int k = 0; k < 2; ++k) dst[n][k] = *(const PG8_LAS bf16x8*)(lds + PG8_SB(b, h) + boff + n * 2048 + k * 1024); } while (0)
; #define PG8_MMA(ai, bj, At, Bt) do { __builtin_amdgcn_s_setprio(1); _Pragma("unroll") for (int m = 0; m < 4; ++m) _Pragma("unroll") for (int n = 0; n < 2; ++n) _Pragma("unroll") for (int k = 0; k < 2; ++k) \
;         acc[ai][bj][m][n] = __builtin_amdgcn_mfma_f32_16x16x32_bf16(Bt[n][k], At[m][k], acc[ai][bj][m][n], 0, 0, 0); __builtin_amdgcn_s_setprio(0); } while (0)
; #define PG8_WAIT_V(n) asm volatile("s_waitcnt vmcnt(" #n ")" ::: "memory")
; #define PG8_WAIT_L(n) asm volatile("s_waitcnt lgkmcnt(" #n ")" ::: "memory")
; #define PG8_BAR __builtin_amdgcn_s_barrier()
; #define PG8_SCHED __builtin_amdgcn_sched_barrier(0)
; template <class Epi, class Sched, bool ALIGN_EPI = false, bool SP2 = false>
; __device__ __forceinline__ void gemm_phase(PG8_LAS unsigned char* lds, const Gemm g, const Sched& S, const Epi& E) {
;     ...
;             PG8_WAIT_V(8); PG8_WAIT_L(0); PG8_BAR; PG8_MMA(1, 0, At, B0); PG8_MMA(1, 1, At, B1); PG8_BAR; PG8_SCHED;
;             PG8_LDB(B0, 1, 0); PG8_LDB(B1, 1, 1); PG8_SCHED; PG8_LDA(At, 1, 0); PG8_STAGE(PG8_SA(0, 1), a2 + hstep, voffA);
;             PG8_WAIT_V(8); PG8_WAIT_L(0); PG8_BAR; PG8_MMA(0, 0, At, B0); PG8_MMA(0, 1, At, B1); PG8_BAR; PG8_SCHED;
	s_setprio 1
	s_waitcnt lgkmcnt(0)
	v_mfma_f32_16x16x32_bf16 v[62:65], v[140:143], v[178:181], v[62:65]
	v_mfma_f32_16x16x32_bf16 v[58:61], v[154:157], v[178:181], v[58:61]
	v_mfma_f32_16x16x32_bf16 v[46:49], v[140:143], v[186:189], v[46:49]
	v_mfma_f32_16x16x32_bf16 v[42:45], v[154:157], v[186:189], v[42:45]
	v_mfma_f32_16x16x32_bf16 v[30:33], v[140:143], v[194:197], v[30:33]
	v_mfma_f32_16x16x32_bf16 v[26:29], v[154:157], v[194:197], v[26:29]
	v_mfma_f32_16x16x32_bf16 v[14:17], v[140:143], v[202:205], v[14:17]
	v_mfma_f32_16x16x32_bf16 v[10:13], v[154:157], v[202:205], v[10:13]
	v_mfma_f32_16x16x32_bf16 v[62:65], v[150:153], v[182:185], v[62:65]
	v_mfma_f32_16x16x32_bf16 v[58:61], v[158:161], v[182:185], v[58:61]
	v_mfma_f32_16x16x32_bf16 v[46:49], v[150:153], v[190:193], v[46:49]
	v_mfma_f32_16x16x32_bf16 v[42:45], v[158:161], v[190:193], v[42:45]
	v_mfma_f32_16x16x32_bf16 v[30:33], v[150:153], v[198:201], v[30:33]
	v_mfma_f32_16x16x32_bf16 v[26:29], v[158:161], v[198:201], v[26:29]
	v_mfma_f32_16x16x32_bf16 v[14:17], v[150:153], v[208:211], v[14:17]
	v_mfma_f32_16x16x32_bf16 v[10:13], v[158:161], v[208:211], v[10:13]
	s_setprio 0
	s_setprio 1
	v_mfma_f32_16x16x32_bf16 v[54:57], v[162:165], v[178:181], v[54:57]
	v_mfma_f32_16x16x32_bf16 v[50:53], v[170:173], v[178:181], v[50:53]
	v_mfma_f32_16x16x32_bf16 v[38:41], v[162:165], v[186:189], v[38:41]
	v_mfma_f32_16x16x32_bf16 v[34:37], v[170:173], v[186:189], v[34:37]
	v_mfma_f32_16x16x32_bf16 v[22:25], v[162:165], v[194:197], v[22:25]
	v_mfma_f32_16x16x32_bf16 v[18:21], v[170:173], v[194:197], v[18:21]
	v_mfma_f32_16x16x32_bf16 v[6:9], v[162:165], v[202:205], v[6:9]
	v_mfma_f32_16x16x32_bf16 v[2:5], v[170:173], v[202:205], v[2:5]
	v_mfma_f32_16x16x32_bf16 v[54:57], v[166:169], v[182:185], v[54:57]
	v_mfma_f32_16x16x32_bf16 v[50:53], v[174:177], v[182:185], v[50:53]
	v_mfma_f32_16x16x32_bf16 v[38:41], v[166:169], v[190:193], v[38:41]
	v_mfma_f32_16x16x32_bf16 v[34:37], v[174:177], v[190:193], v[34:37]
	v_mfma_f32_16x16x32_bf16 v[22:25], v[166:169], v[198:201], v[22:25]
	v_mfma_f32_16x16x32_bf16 v[18:21], v[174:177], v[198:201], v[18:21]
	v_mfma_f32_16x16x32_bf16 v[6:9], v[166:169], v[208:211], v[6:9]
	v_mfma_f32_16x16x32_bf16 v[2:5], v[174:177], v[208:211], v[2:5]
	s_setprio 0
	s_barrier
	s_add_i32 s79, 0, 0x18000
	v_add_u32_e32 v144, s79, v146
	s_add_i32 s85, 0, 0x1c000
	ds_read_b128 v[140:143], v144
	ds_read_b128 v[150:153], v144 offset:1024
	ds_read_b128 v[154:157], v144 offset:2048
	ds_read_b128 v[158:161], v144 offset:3072
	v_add_u32_e32 v144, s85, v146
	ds_read_b128 v[162:165], v144
	ds_read_b128 v[166:169], v144 offset:1024
	ds_read_b128 v[170:173], v144 offset:2048
	ds_read_b128 v[174:177], v144 offset:3072
	s_add_u32 s90, s90, 0x40000
	s_addc_u32 s91, s91, 0
	s_mov_b32 m0, s29
	v_lshl_add_u64 v[220:221], s[90:91], 0, v[130:131]
	ds_read_b128 v[178:181], v149 offset:32768
	ds_read_b128 v[182:185], v149 offset:33792
	ds_read_b128 v[186:189], v149 offset:34816
	ds_read_b128 v[190:193], v149 offset:35840
	ds_read_b128 v[194:197], v149 offset:36864
	ds_read_b128 v[198:201], v149 offset:37888
	ds_read_b128 v[202:205], v149 offset:38912
	ds_read_b128 v[208:211], v149 offset:39936
	global_load_lds_dwordx4 v[220:221], off
	v_lshl_add_u64 v[220:221], s[90:91], 0, v[132:133]
	s_mov_b32 m0, s42
	s_nop 0
	global_load_lds_dwordx4 v[220:221], off
	s_waitcnt vmcnt(8)
	s_waitcnt lgkmcnt(0)
	s_barrier
	s_setprio 1
	s_waitcnt lgkmcnt(0)
	v_mfma_f32_16x16x32_bf16 v[126:129], v[140:143], v[178:181], v[126:129]
	v_mfma_f32_16x16x32_bf16 v[122:125], v[154:157], v[178:181], v[122:125]
	v_mfma_f32_16x16x32_bf16 v[110:113], v[140:143], v[186:189], v[110:113]
	v_mfma_f32_16x16x32_bf16 v[106:109], v[154:157], v[186:189], v[106:109]
	v_mfma_f32_16x16x32_bf16 v[94:97], v[140:143], v[194:197], v[94:97]
	v_mfma_f32_16x16x32_bf16 v[90:93], v[154:157], v[194:197], v[90:93]
	v_mfma_f32_16x16x32_bf16 v[78:81], v[140:143], v[202:205], v[78:81]
	v_mfma_f32_16x16x32_bf16 v[74:77], v[154:157], v[202:205], v[74:77]
	v_mfma_f32_16x16x32_bf16 v[126:129], v[150:153], v[182:185], v[126:129]
	v_mfma_f32_16x16x32_bf16 v[122:125], v[158:161], v[182:185], v[122:125]
	v_mfma_f32_16x16x32_bf16 v[110:113], v[150:153], v[190:193], v[110:113]
	v_mfma_f32_16x16x32_bf16 v[106:109], v[158:161], v[190:193], v[106:109]
	v_mfma_f32_16x16x32_bf16 v[94:97], v[150:153], v[198:201], v[94:97]
	v_mfma_f32_16x16x32_bf16 v[90:93], v[158:161], v[198:201], v[90:93]
	v_mfma_f32_16x16x32_bf16 v[78:81], v[150:153], v[208:211], v[78:81]
	v_mfma_f32_16x16x32_bf16 v[74:77], v[158:161], v[208:211], v[74:77]
	s_setprio 0
	s_setprio 1
	v_mfma_f32_16x16x32_bf16 v[118:121], v[162:165], v[178:181], v[118:121]
	v_mfma_f32_16x16x32_bf16 v[114:117], v[170:173], v[178:181], v[114:117]
	v_mfma_f32_16x16x32_bf16 v[102:105], v[162:165], v[186:189], v[102:105]
	v_mfma_f32_16x16x32_bf16 v[98:101], v[170:173], v[186:189], v[98:101]
	v_mfma_f32_16x16x32_bf16 v[86:89], v[162:165], v[194:197], v[86:89]
	v_mfma_f32_16x16x32_bf16 v[82:85], v[170:173], v[194:197], v[82:85]
	v_mfma_f32_16x16x32_bf16 v[70:73], v[162:165], v[202:205], v[70:73]
	v_mfma_f32_16x16x32_bf16 v[66:69], v[170:173], v[202:205], v[66:69]
	v_mfma_f32_16x16x32_bf16 v[118:121], v[166:169], v[182:185], v[118:121]
	v_mfma_f32_16x16x32_bf16 v[114:117], v[174:177], v[182:185], v[114:117]
	v_mfma_f32_16x16x32_bf16 v[102:105], v[166:169], v[190:193], v[102:105]
	v_mfma_f32_16x16x32_bf16 v[98:101], v[174:177], v[190:193], v[98:101]
	v_mfma_f32_16x16x32_bf16 v[86:89], v[166:169], v[198:201], v[86:89]
	v_mfma_f32_16x16x32_bf16 v[82:85], v[174:177], v[198:201], v[82:85]
	v_mfma_f32_16x16x32_bf16 v[70:73], v[166:169], v[208:211], v[70:73]
	v_mfma_f32_16x16x32_bf16 v[66:69], v[174:177], v[208:211], v[66:69]
	s_setprio 0
	s_barrier
; #define PG8_STAGE(bufoff, gbase, voff) do { _Pragma("unroll") for (int _i = 0; _i < 2; ++_i) \
;         __builtin_amdgcn_global_load_lds((const unsigned*)((const char*)(gbase) + (voff)[_i]), (PG8_LAS unsigned*)(lds + (bufoff) + ldsw + _i * 8192), 16, 0, 0); } while (0)
; #define PG8_LDA(dst, b, h) do { _Pragma("unroll") for (int m = 0; m < 4; ++m) _Pragma("unroll") for (int k = 0; k < 2; ++k) dst[m][k] = *(const PG8_LAS bf16x8*)(lds + PG8_SA(b, h) + aoff + m * 2048 + k * 1024); } while (0)
; #define PG8_MMA(ai, bj, At, Bt) do { __builtin_amdgcn_s_setprio(1); _Pragma("unroll") for (int m = 0; m < 4; ++m) _Pragma("unroll") for (int n = 0; n < 2; ++n) _Pragma("unroll") for (int k = 0; k < 2; ++k) \
;         acc[ai][bj][m][n] = __builtin_amdgcn_mfma_f32_16x16x32_bf16(Bt[n][k], At[m][k], acc[ai][bj][m][n], 0, 0, 0); __builtin_amdgcn_s_setprio(0); } while (0)
; #define PG8_WAIT_V(n) asm volatile("s_waitcnt vmcnt(" #n ")" ::: "memory")
; #define PG8_WAIT_L(n) asm volatile("s_waitcnt lgkmcnt(" #n ")" ::: "memory")
; #define PG8_BAR __builtin_amdgcn_s_barrier()
; #define PG8_SCHED __builtin_amdgcn_sched_barrier(0)
; template <class Epi, class Sched, bool ALIGN_EPI = false, bool SP2 = false>
; __device__ __forceinline__ void gemm_phase(PG8_LAS unsigned char* lds, const Gemm g, const Sched& S, const Epi& E) {
;     ...
;             PG8_LDA(At, 1, 1); PG8_STAGE(PG8_SB(1, 0), b3, voffB); PG8_STAGE(PG8_SB(1, 1), b3 + hstep, voffB); PG8_STAGE(PG8_SA(1, 0), a3, voffA);
;             PG8_WAIT_V(8); PG8_WAIT_L(0); PG8_BAR; PG8_MMA(1, 0, At, B0); PG8_MMA(1, 1, At, B1); PG8_BAR; PG8_SCHED;
	s_add_i32 s79, s79, s14
	v_lshl_add_u64 v[212:213], v[212:213], 0, s[24:25]
	s_mov_b32 m0, s79
	ds_read_b128 v[178:181], v149 offset:49152
	ds_read_b128 v[182:185], v149 offset:50176
	ds_read_b128 v[186:189], v149 offset:51200
	ds_read_b128 v[190:193], v149 offset:52224
	ds_read_b128 v[194:197], v149 offset:53248
	ds_read_b128 v[198:201], v149 offset:54272
	ds_read_b128 v[202:205], v149 offset:55296
	ds_read_b128 v[208:211], v149 offset:56320
	global_load_lds_dwordx4 v[212:213], off
	s_add_i32 m0, s79, 0x2000
	s_add_u32 s88, s88, 0x40080
	v_lshl_add_u64 v[212:213], v[214:215], 0, s[24:25]
	s_addc_u32 s89, s89, 0
	s_add_i32 s79, s85, s14
	global_load_lds_dwordx4 v[212:213], off
	v_lshl_add_u64 v[212:213], s[88:89], 0, v[0:1]
	s_mov_b32 m0, s79
	s_nop 0
	global_load_lds_dwordx4 v[212:213], off
	v_lshl_add_u64 v[212:213], s[88:89], 0, v[134:135]
	s_add_i32 m0, s79, 0x2000
	s_nop 0
	global_load_lds_dwordx4 v[212:213], off
	v_lshl_add_u64 v[212:213], v[216:217], 0, s[24:25]
	s_mov_b32 m0, s43
	s_nop 0
	global_load_lds_dwordx4 v[212:213], off
	v_lshl_add_u64 v[212:213], v[218:219], 0, s[24:25]
	s_mov_b32 m0, s44
	s_nop 0
	global_load_lds_dwordx4 v[212:213], off
	s_waitcnt vmcnt(8)
	s_waitcnt lgkmcnt(0)
	s_barrier
	s_setprio 1
	s_waitcnt lgkmcnt(0)
	v_mfma_f32_16x16x32_bf16 v[62:65], v[140:143], v[178:181], v[62:65]
	v_mfma_f32_16x16x32_bf16 v[58:61], v[154:157], v[178:181], v[58:61]
	v_mfma_f32_16x16x32_bf16 v[46:49], v[140:143], v[186:189], v[46:49]
	v_mfma_f32_16x16x32_bf16 v[42:45], v[154:157], v[186:189], v[42:45]
	v_mfma_f32_16x16x32_bf16 v[30:33], v[140:143], v[194:197], v[30:33]
	v_mfma_f32_16x16x32_bf16 v[26:29], v[154:157], v[194:197], v[26:29]
	v_mfma_f32_16x16x32_bf16 v[14:17], v[140:143], v[202:205], v[14:17]
	v_mfma_f32_16x16x32_bf16 v[10:13], v[154:157], v[202:205], v[10:13]
	v_mfma_f32_16x16x32_bf16 v[62:65], v[150:153], v[182:185], v[62:65]
	v_mfma_f32_16x16x32_bf16 v[58:61], v[158:161], v[182:185], v[58:61]
	v_mfma_f32_16x16x32_bf16 v[46:49], v[150:153], v[190:193], v[46:49]
	v_mfma_f32_16x16x32_bf16 v[42:45], v[158:161], v[190:193], v[42:45]
	v_mfma_f32_16x16x32_bf16 v[30:33], v[150:153], v[198:201], v[30:33]
	v_mfma_f32_16x16x32_bf16 v[26:29], v[158:161], v[198:201], v[26:29]
	v_mfma_f32_16x16x32_bf16 v[14:17], v[150:153], v[208:211], v[14:17]
	v_mfma_f32_16x16x32_bf16 v[10:13], v[158:161], v[208:211], v[10:13]
	s_setprio 0
	s_setprio 1
	v_mfma_f32_16x16x32_bf16 v[54:57], v[162:165], v[178:181], v[54:57]
	v_mfma_f32_16x16x32_bf16 v[50:53], v[170:173], v[178:181], v[50:53]
	v_mfma_f32_16x16x32_bf16 v[38:41], v[162:165], v[186:189], v[38:41]
	v_mfma_f32_16x16x32_bf16 v[34:37], v[170:173], v[186:189], v[34:37]
	v_mfma_f32_16x16x32_bf16 v[22:25], v[162:165], v[194:197], v[22:25]
	v_mfma_f32_16x16x32_bf16 v[18:21], v[170:173], v[194:197], v[18:21]
	v_mfma_f32_16x16x32_bf16 v[6:9], v[162:165], v[202:205], v[6:9]
	v_mfma_f32_16x16x32_bf16 v[2:5], v[170:173], v[202:205], v[2:5]
	v_mfma_f32_16x16x32_bf16 v[54:57], v[166:169], v[182:185], v[54:57]
	v_mfma_f32_16x16x32_bf16 v[50:53], v[174:177], v[182:185], v[50:53]
	v_mfma_f32_16x16x32_bf16 v[38:41], v[166:169], v[190:193], v[38:41]
	v_mfma_f32_16x16x32_bf16 v[34:37], v[174:177], v[190:193], v[34:37]
	v_mfma_f32_16x16x32_bf16 v[22:25], v[166:169], v[198:201], v[22:25]
	v_mfma_f32_16x16x32_bf16 v[18:21], v[174:177], v[198:201], v[18:21]
	v_mfma_f32_16x16x32_bf16 v[6:9], v[166:169], v[208:211], v[6:9]
	v_mfma_f32_16x16x32_bf16 v[2:5], v[174:177], v[208:211], v[2:5]
	s_setprio 0
	s_add_i32 s77, s77, 2
	s_add_u32 s86, s86, 0x100
	s_addc_u32 s87, s87, 0
	s_add_u32 s64, s64, 0x100
	s_addc_u32 s65, s65, 0
	s_cmp_gt_u32 s77, 13
	s_barrier
	s_cbranch_scc0 .LBB0_242
	s_and_b64 vcc, exec, s[74:75]
	s_cbranch_vccz .LBB0_245
	s_barrier

; #define PG8_STAGE(bufoff, gbase, voff) do { _Pragma("unroll") for (int _i = 0; _i < 2; ++_i) \
;         __builtin_amdgcn_global_load_lds((const unsigned*)((const char*)(gbase) + (voff)[_i]), (PG8_LAS unsigned*)(lds + (bufoff) + ldsw + _i * 8192), 16, 0, 0); } while (0)
; #define PG8_LDA(dst, b, h) do { _Pragma("unroll") for (int m = 0; m < 4; ++m) _Pragma("unroll") for (int k = 0; k < 2; ++k) dst[m][k] = *(const PG8_LAS bf16x8*)(lds + PG8_SA(b, h) + aoff + m * 2048 + k * 1024); } while (0)
; #define PG8_LDB(dst, b, h) do { _Pragma("unroll") for (int n = 0; n < 2; ++n) _Pragma("unroll") for (int k = 0; k < 2; ++k) dst[n][k] = *(const PG8_LAS bf16x8*)(lds + PG8_SB(b, h) + boff + n * 2048 + k * 1024); } while (0)
; #define PG8_MMA(ai, bj, At, Bt) do { __builtin_amdgcn_s_setprio(1); _Pragma("unroll") for (int m = 0; m < 4; ++m) _Pragma("unroll") for (int n = 0; n < 2; ++n) _Pragma("unroll") for (int k = 0; k < 2; ++k) \
;         acc[ai][bj][m][n] = __builtin_amdgcn_mfma_f32_16x16x32_bf16(Bt[n][k], At[m][k], acc[ai][bj][m][n], 0, 0, 0); __builtin_amdgcn_s_setprio(0); } while (0)
; #define PG8_WAIT_V(n) asm volatile("s_waitcnt vmcnt(" #n ")" ::: "memory")
; #define PG8_WAIT_L(n) asm volatile("s_waitcnt lgkmcnt(" #n ")" ::: "memory")
; template <class Epi, class Sched, bool ALIGN_EPI = false, bool SP2 = false>
; __device__ __forceinline__ void gemm_phase(PG8_LAS unsigned char* lds, const Gemm g, const Sched& S, const Epi& E) {
;     ...
;             const bool last = (t == nt - 2);
;             const char* a1 = cA + (size_t)(t + 1) * kstep;
;             const char* a2 = last ? nA : cA + (size_t)(t + 2) * kstep; const char* b2 = last ? nB : cB + (size_t)(t + 2) * kstep;
;             const char* a3 = a2 + kstep; const char* b3 = b2 + kstep;
;             if (last && has_next) S.a_ready(nxt);
;             if constexpr (SP2) {
;             PG8_LDB(B0, 0, 0); PG8_LDB(B1, 0, 1); PG8_SCHED; PG8_LDA(At, 0, 0); PG8_STAGE(PG8_SA(1, 1), a1 + hstep, voffA);
;             PG8_WAIT_V(8); PG8_WAIT_L(0); PG8_BAR; PG8_MMA(0, 0, At, B0); PG8_MMA(0, 1, At, B1); PG8_BAR; PG8_SCHED;
;             PG8_LDA(At, 0, 1); PG8_STAGE(PG8_SB(0, 0), b2, voffB); PG8_STAGE(PG8_SB(0, 1), b2 + hstep, voffB); PG8_STAGE(PG8_SA(0, 0), a2, voffA);
;             PG8_WAIT_V(8); PG8_WAIT_L(0); PG8_BAR; PG8_MMA(1, 0, At, B0); PG8_MMA(1, 1, At, B1); PG8_BAR; PG8_SCHED;
.LBB0_320:
	s_add_i32 s92, 0, 0x10000
	v_add_u32_e32 v130, s92, v252
	ds_read_b128 v[114:117], v130
	ds_read_b128 v[122:125], v130 offset:1024
	ds_read_b128 v[126:129], v130 offset:2048
	ds_read_b128 v[130:133], v130 offset:3072
	s_add_i32 s67, s66, 2
	s_add_u32 s77, s86, 0x80
	s_addc_u32 s88, s87, 0
	s_cmp_eq_u32 s45, s66
	s_cselect_b32 s89, s9, s88
	s_cselect_b32 s88, s8, s77
	s_cselect_b32 s91, s85, s65
	s_cselect_b32 s90, s84, s64
	s_add_i32 s66, 0, 0x14000
	v_add_u32_e32 v158, s66, v252
	ds_read_b128 v[138:141], v158
	ds_read_b128 v[142:145], v158 offset:1024
	ds_read_b128 v[146:149], v158 offset:2048
	ds_read_b128 v[158:161], v158 offset:3072
	v_lshl_add_u64 v[204:205], s[86:87], 0, v[200:201]
	s_add_i32 m0, s20, 0xc000
	ds_read_b128 v[162:165], v254
	ds_read_b128 v[166:169], v254 offset:1024
	ds_read_b128 v[170:173], v254 offset:2048
	ds_read_b128 v[174:177], v254 offset:3072
	ds_read_b128 v[178:181], v254 offset:4096
	ds_read_b128 v[182:185], v254 offset:5120
	ds_read_b128 v[186:189], v254 offset:6144
	ds_read_b128 v[190:193], v254 offset:7168
	global_load_lds_dwordx4 v[204:205], off
	v_lshl_add_u64 v[204:205], s[86:87], 0, v[202:203]
	s_add_i32 m0, s20, 0xe000
	s_nop 0
	global_load_lds_dwordx4 v[204:205], off
	s_waitcnt vmcnt(8)
	s_waitcnt lgkmcnt(0)
	s_barrier
	s_setprio 1
	s_waitcnt lgkmcnt(0)
	v_mfma_f32_16x16x32_bf16 v[154:157], v[114:117], v[162:165], v[154:157]
	v_mfma_f32_16x16x32_bf16 v[150:153], v[126:129], v[162:165], v[150:153]
	v_mfma_f32_16x16x32_bf16 v[110:113], v[114:117], v[170:173], v[110:113]
	v_mfma_f32_16x16x32_bf16 v[106:109], v[126:129], v[170:173], v[106:109]
	v_mfma_f32_16x16x32_bf16 v[94:97], v[114:117], v[178:181], v[94:97]
	v_mfma_f32_16x16x32_bf16 v[90:93], v[126:129], v[178:181], v[90:93]
	v_mfma_f32_16x16x32_bf16 v[78:81], v[114:117], v[186:189], v[78:81]
	v_mfma_f32_16x16x32_bf16 v[74:77], v[126:129], v[186:189], v[74:77]
	v_mfma_f32_16x16x32_bf16 v[154:157], v[122:125], v[166:169], v[154:157]
	v_mfma_f32_16x16x32_bf16 v[150:153], v[130:133], v[166:169], v[150:153]
	v_mfma_f32_16x16x32_bf16 v[110:113], v[122:125], v[174:177], v[110:113]
	v_mfma_f32_16x16x32_bf16 v[106:109], v[130:133], v[174:177], v[106:109]
	v_mfma_f32_16x16x32_bf16 v[94:97], v[122:125], v[182:185], v[94:97]
	v_mfma_f32_16x16x32_bf16 v[90:93], v[130:133], v[182:185], v[90:93]
	v_mfma_f32_16x16x32_bf16 v[78:81], v[122:125], v[190:193], v[78:81]
	v_mfma_f32_16x16x32_bf16 v[74:77], v[130:133], v[190:193], v[74:77]
	s_setprio 0
	s_setprio 1
	v_mfma_f32_16x16x32_bf16 v[134:137], v[138:141], v[162:165], v[134:137]
	v_mfma_f32_16x16x32_bf16 v[118:121], v[146:149], v[162:165], v[118:121]
	v_mfma_f32_16x16x32_bf16 v[102:105], v[138:141], v[170:173], v[102:105]
	v_mfma_f32_16x16x32_bf16 v[98:101], v[146:149], v[170:173], v[98:101]
	v_mfma_f32_16x16x32_bf16 v[86:89], v[138:141], v[178:181], v[86:89]
	v_mfma_f32_16x16x32_bf16 v[82:85], v[146:149], v[178:181], v[82:85]
	v_mfma_f32_16x16x32_bf16 v[70:73], v[138:141], v[186:189], v[70:73]
	v_mfma_f32_16x16x32_bf16 v[66:69], v[146:149], v[186:189], v[66:69]
	v_mfma_f32_16x16x32_bf16 v[134:137], v[142:145], v[166:169], v[134:137]
	v_mfma_f32_16x16x32_bf16 v[118:121], v[158:161], v[166:169], v[118:121]
	v_mfma_f32_16x16x32_bf16 v[102:105], v[142:145], v[174:177], v[102:105]
	v_mfma_f32_16x16x32_bf16 v[98:101], v[158:161], v[174:177], v[98:101]
	v_mfma_f32_16x16x32_bf16 v[86:89], v[142:145], v[182:185], v[86:89]
	v_mfma_f32_16x16x32_bf16 v[82:85], v[158:161], v[182:185], v[82:85]
	v_mfma_f32_16x16x32_bf16 v[70:73], v[142:145], v[190:193], v[70:73]
	v_mfma_f32_16x16x32_bf16 v[66:69], v[158:161], v[190:193], v[66:69]
	s_setprio 0
	s_barrier
	s_add_i32 s77, s92, s15
	v_lshl_add_u64 v[204:205], s[90:91], 0, v[0:1]
	s_mov_b32 m0, s77
	ds_read_b128 v[162:165], v254 offset:16384
	ds_read_b128 v[166:169], v254 offset:17408
	ds_read_b128 v[170:173], v254 offset:18432
	ds_read_b128 v[174:177], v254 offset:19456
	ds_read_b128 v[178:181], v254 offset:20480
	ds_read_b128 v[182:185], v254 offset:21504
	ds_read_b128 v[186:189], v254 offset:22528
	ds_read_b128 v[190:193], v254 offset:23552
	global_load_lds_dwordx4 v[204:205], off
	s_add_i32 m0, s77, 0x2000
	v_lshl_add_u64 v[208:209], s[90:91], 0, v[198:199]
	s_add_u32 s90, s90, s76
	s_addc_u32 s91, s91, 0
	s_add_i32 s66, s66, s15
	global_load_lds_dwordx4 v[208:209], off
	v_lshl_add_u64 v[210:211], s[90:91], 0, v[0:1]
	s_mov_b32 m0, s66
	v_lshl_add_u64 v[212:213], s[90:91], 0, v[198:199]
	global_load_lds_dwordx4 v[210:211], off
	s_add_i32 m0, s66, 0x2000
	v_lshl_add_u64 v[214:215], s[88:89], 0, v[194:195]
	global_load_lds_dwordx4 v[212:213], off
	s_mov_b32 m0, s20
	v_lshl_add_u64 v[216:217], s[88:89], 0, v[196:197]
	global_load_lds_dwordx4 v[214:215], off
	s_mov_b32 m0, s26
	s_nop 0
	global_load_lds_dwordx4 v[216:217], off
	s_waitcnt vmcnt(8)
	s_waitcnt lgkmcnt(0)
	s_barrier
; #define PG8_STAGE(bufoff, gbase, voff) do { _Pragma("unroll") for (int _i = 0; _i < 2; ++_i) \
;         __builtin_amdgcn_global_load_lds((const unsigned*)((const char*)(gbase) + (voff)[_i]), (PG8_LAS unsigned*)(lds + (bufoff) + ldsw + _i * 8192), 16, 0, 0); } while (0)
; #define PG8_LDA(dst, b, h) do { _Pragma("unroll") for (int m = 0; m < 4; ++m) _Pragma("unroll") for (int k = 0; k < 2; ++k) dst[m][k] = *(const PG8_LAS bf16x8*)(lds + PG8_SA(b, h) + aoff + m * 2048 + k * 1024); } while (0)
; #define PG8_LDB(dst, b, h) do { _Pragma("unroll") for (int n = 0; n < 2; ++n) _Pragma("unroll") for (int k = 0; k < 2; ++k) dst[n][k] = *(const PG8_LAS bf16x8*)(lds + PG8_SB(b, h) + boff + n * 2048 + k * 1024); } while (0)
; #define PG8_MMA(ai, bj, At, Bt) do { __builtin_amdgcn_s_setprio(1); _Pragma("unroll") for (int m = 0; m < 4; ++m) _Pragma("unroll") for (int n = 0; n < 2; ++n) _Pragma("unroll") for (int k = 0; k < 2; ++k) \
;         acc[ai][bj][m][n] = __builtin_amdgcn_mfma_f32_16x16x32_bf16(Bt[n][k], At[m][k], acc[ai][bj][m][n], 0, 0, 0); __builtin_amdgcn_s_setprio(0); } while (0)
; #define PG8_WAIT_V(n) asm volatile("s_waitcnt vmcnt(" #n ")" ::: "memory")
; #define PG8_WAIT_L(n) asm volatile("s_waitcnt lgkmcnt(" #n ")" ::: "memory")
; #define PG8_BAR __builtin_amdgcn_s_barrier()
; #define PG8_SCHED __builtin_amdgcn_sched_barrier(0)
; template <class Epi, class Sched, bool ALIGN_EPI = false, bool SP2 = false>
; __device__ __forceinline__ void gemm_phase(PG8_LAS unsigned char* lds, const Gemm g, const Sched& S, const Epi& E) {
;     ...
;             PG8_WAIT_V(8); PG8_WAIT_L(0); PG8_BAR; PG8_MMA(1, 0, At, B0); PG8_MMA(1, 1, At, B1); PG8_BAR; PG8_SCHED;
;             PG8_LDB(B0, 1, 0); PG8_LDB(B1, 1, 1); PG8_SCHED; PG8_LDA(At, 1, 0); PG8_STAGE(PG8_SA(0, 1), a2 + hstep, voffA);
;             PG8_WAIT_V(8); PG8_WAIT_L(0); PG8_BAR; PG8_MMA(0, 0, At, B0); PG8_MMA(0, 1, At, B1); PG8_BAR; PG8_SCHED;
	s_setprio 1
	s_waitcnt lgkmcnt(0)
	v_mfma_f32_16x16x32_bf16 v[62:65], v[114:117], v[162:165], v[62:65]
	v_mfma_f32_16x16x32_bf16 v[58:61], v[126:129], v[162:165], v[58:61]
	v_mfma_f32_16x16x32_bf16 v[46:49], v[114:117], v[170:173], v[46:49]
	v_mfma_f32_16x16x32_bf16 v[42:45], v[126:129], v[170:173], v[42:45]
	v_mfma_f32_16x16x32_bf16 v[30:33], v[114:117], v[178:181], v[30:33]
	v_mfma_f32_16x16x32_bf16 v[26:29], v[126:129], v[178:181], v[26:29]
	v_mfma_f32_16x16x32_bf16 v[14:17], v[114:117], v[186:189], v[14:17]
	v_mfma_f32_16x16x32_bf16 v[10:13], v[126:129], v[186:189], v[10:13]
	v_mfma_f32_16x16x32_bf16 v[62:65], v[122:125], v[166:169], v[62:65]
	v_mfma_f32_16x16x32_bf16 v[58:61], v[130:133], v[166:169], v[58:61]
	v_mfma_f32_16x16x32_bf16 v[46:49], v[122:125], v[174:177], v[46:49]
	v_mfma_f32_16x16x32_bf16 v[42:45], v[130:133], v[174:177], v[42:45]
	v_mfma_f32_16x16x32_bf16 v[30:33], v[122:125], v[182:185], v[30:33]
	v_mfma_f32_16x16x32_bf16 v[26:29], v[130:133], v[182:185], v[26:29]
	v_mfma_f32_16x16x32_bf16 v[14:17], v[122:125], v[190:193], v[14:17]
	v_mfma_f32_16x16x32_bf16 v[10:13], v[130:133], v[190:193], v[10:13]
	s_setprio 0
	s_setprio 1
	v_mfma_f32_16x16x32_bf16 v[54:57], v[138:141], v[162:165], v[54:57]
	v_mfma_f32_16x16x32_bf16 v[50:53], v[146:149], v[162:165], v[50:53]
	v_mfma_f32_16x16x32_bf16 v[38:41], v[138:141], v[170:173], v[38:41]
	v_mfma_f32_16x16x32_bf16 v[34:37], v[146:149], v[170:173], v[34:37]
	v_mfma_f32_16x16x32_bf16 v[22:25], v[138:141], v[178:181], v[22:25]
	v_mfma_f32_16x16x32_bf16 v[18:21], v[146:149], v[178:181], v[18:21]
	v_mfma_f32_16x16x32_bf16 v[6:9], v[138:141], v[186:189], v[6:9]
	v_mfma_f32_16x16x32_bf16 v[2:5], v[146:149], v[186:189], v[2:5]
	v_mfma_f32_16x16x32_bf16 v[54:57], v[142:145], v[166:169], v[54:57]
	v_mfma_f32_16x16x32_bf16 v[50:53], v[158:161], v[166:169], v[50:53]
	v_mfma_f32_16x16x32_bf16 v[38:41], v[142:145], v[174:177], v[38:41]
	v_mfma_f32_16x16x32_bf16 v[34:37], v[158:161], v[174:177], v[34:37]
	v_mfma_f32_16x16x32_bf16 v[22:25], v[142:145], v[182:185], v[22:25]
	v_mfma_f32_16x16x32_bf16 v[18:21], v[158:161], v[182:185], v[18:21]
	v_mfma_f32_16x16x32_bf16 v[6:9], v[142:145], v[190:193], v[6:9]
	v_mfma_f32_16x16x32_bf16 v[2:5], v[158:161], v[190:193], v[2:5]
	s_setprio 0
	s_barrier
	s_add_i32 s66, 0, 0x18000
	s_add_i32 s77, 0, 0x1c000
	v_add_u32_e32 v130, s66, v252
	v_add_u32_e32 v158, s77, v252
	ds_read_b128 v[114:117], v130
	ds_read_b128 v[122:125], v130 offset:1024
	ds_read_b128 v[126:129], v130 offset:2048
	ds_read_b128 v[130:133], v130 offset:3072
	ds_read_b128 v[138:141], v158
	ds_read_b128 v[142:145], v158 offset:1024
	ds_read_b128 v[146:149], v158 offset:2048
	ds_read_b128 v[158:161], v158 offset:3072
	s_add_u32 s88, s88, s76
	s_addc_u32 s89, s89, 0
	s_mov_b32 m0, s27
	v_lshl_add_u64 v[218:219], s[88:89], 0, v[194:195]
	ds_read_b128 v[162:165], v254 offset:32768
	ds_read_b128 v[166:169], v254 offset:33792
	ds_read_b128 v[170:173], v254 offset:34816
	ds_read_b128 v[174:177], v254 offset:35840
	ds_read_b128 v[178:181], v254 offset:36864
	ds_read_b128 v[182:185], v254 offset:37888
	ds_read_b128 v[186:189], v254 offset:38912
	ds_read_b128 v[190:193], v254 offset:39936
	global_load_lds_dwordx4 v[218:219], off
	v_lshl_add_u64 v[218:219], s[88:89], 0, v[196:197]
	s_mov_b32 m0, s28
	s_nop 0
	global_load_lds_dwordx4 v[218:219], off
	s_waitcnt vmcnt(8)
	s_waitcnt lgkmcnt(0)
	s_barrier
	s_setprio 1
	s_waitcnt lgkmcnt(0)
	v_mfma_f32_16x16x32_bf16 v[154:157], v[114:117], v[162:165], v[154:157]
	v_mfma_f32_16x16x32_bf16 v[150:153], v[126:129], v[162:165], v[150:153]
	v_mfma_f32_16x16x32_bf16 v[110:113], v[114:117], v[170:173], v[110:113]
	v_mfma_f32_16x16x32_bf16 v[106:109], v[126:129], v[170:173], v[106:109]
	v_mfma_f32_16x16x32_bf16 v[94:97], v[114:117], v[178:181], v[94:97]
	v_mfma_f32_16x16x32_bf16 v[90:93], v[126:129], v[178:181], v[90:93]
	v_mfma_f32_16x16x32_bf16 v[78:81], v[114:117], v[186:189], v[78:81]
	v_mfma_f32_16x16x32_bf16 v[74:77], v[126:129], v[186:189], v[74:77]
	v_mfma_f32_16x16x32_bf16 v[154:157], v[122:125], v[166:169], v[154:157]
	v_mfma_f32_16x16x32_bf16 v[150:153], v[130:133], v[166:169], v[150:153]
	v_mfma_f32_16x16x32_bf16 v[110:113], v[122:125], v[174:177], v[110:113]
	v_mfma_f32_16x16x32_bf16 v[106:109], v[130:133], v[174:177], v[106:109]
	v_mfma_f32_16x16x32_bf16 v[94:97], v[122:125], v[182:185], v[94:97]
	v_mfma_f32_16x16x32_bf16 v[90:93], v[130:133], v[182:185], v[90:93]
	v_mfma_f32_16x16x32_bf16 v[78:81], v[122:125], v[190:193], v[78:81]
	v_mfma_f32_16x16x32_bf16 v[74:77], v[130:133], v[190:193], v[74:77]
	s_setprio 0
	s_setprio 1
	v_mfma_f32_16x16x32_bf16 v[134:137], v[138:141], v[162:165], v[134:137]
	v_mfma_f32_16x16x32_bf16 v[118:121], v[146:149], v[162:165], v[118:121]
	v_mfma_f32_16x16x32_bf16 v[102:105], v[138:141], v[170:173], v[102:105]
	v_mfma_f32_16x16x32_bf16 v[98:101], v[146:149], v[170:173], v[98:101]
	v_mfma_f32_16x16x32_bf16 v[86:89], v[138:141], v[178:181], v[86:89]
	v_mfma_f32_16x16x32_bf16 v[82:85], v[146:149], v[178:181], v[82:85]
	v_mfma_f32_16x16x32_bf16 v[70:73], v[138:141], v[186:189], v[70:73]
	v_mfma_f32_16x16x32_bf16 v[66:69], v[146:149], v[186:189], v[66:69]
	v_mfma_f32_16x16x32_bf16 v[134:137], v[142:145], v[166:169], v[134:137]
	v_mfma_f32_16x16x32_bf16 v[118:121], v[158:161], v[166:169], v[118:121]
	v_mfma_f32_16x16x32_bf16 v[102:105], v[142:145], v[174:177], v[102:105]
	v_mfma_f32_16x16x32_bf16 v[98:101], v[158:161], v[174:177], v[98:101]
	v_mfma_f32_16x16x32_bf16 v[86:89], v[142:145], v[182:185], v[86:89]
	v_mfma_f32_16x16x32_bf16 v[82:85], v[158:161], v[182:185], v[82:85]
	v_mfma_f32_16x16x32_bf16 v[70:73], v[142:145], v[190:193], v[70:73]
	v_mfma_f32_16x16x32_bf16 v[66:69], v[158:161], v[190:193], v[66:69]
	s_setprio 0
	s_barrier
; #define PG8_STAGE(bufoff, gbase, voff) do { _Pragma("unroll") for (int _i = 0; _i < 2; ++_i) \
;         __builtin_amdgcn_global_load_lds((const unsigned*)((const char*)(gbase) + (voff)[_i]), (PG8_LAS unsigned*)(lds + (bufoff) + ldsw + _i * 8192), 16, 0, 0); } while (0)
; #define PG8_LDA(dst, b, h) do { _Pragma("unroll") for (int m = 0; m < 4; ++m) _Pragma("unroll") for (int k = 0; k < 2; ++k) dst[m][k] = *(const PG8_LAS bf16x8*)(lds + PG8_SA(b, h) + aoff + m * 2048 + k * 1024); } while (0)
; #define PG8_MMA(ai, bj, At, Bt) do { __builtin_amdgcn_s_setprio(1); _Pragma("unroll") for (int m = 0; m < 4; ++m) _Pragma("unroll") for (int n = 0; n < 2; ++n) _Pragma("unroll") for (int k = 0; k < 2; ++k) \
;         acc[ai][bj][m][n] = __builtin_amdgcn_mfma_f32_16x16x32_bf16(Bt[n][k], At[m][k], acc[ai][bj][m][n], 0, 0, 0); __builtin_amdgcn_s_setprio(0); } while (0)
; #define PG8_WAIT_V(n) asm volatile("s_waitcnt vmcnt(" #n ")" ::: "memory")
; #define PG8_WAIT_L(n) asm volatile("s_waitcnt lgkmcnt(" #n ")" ::: "memory")
; #define PG8_BAR __builtin_amdgcn_s_barrier()
; #define PG8_SCHED __builtin_amdgcn_sched_barrier(0)
; template <class Epi, class Sched, bool ALIGN_EPI = false, bool SP2 = false>
; __device__ __forceinline__ void gemm_phase(PG8_LAS unsigned char* lds, const Gemm g, const Sched& S, const Epi& E) {
;     ...
;             PG8_LDA(At, 1, 1); PG8_STAGE(PG8_SB(1, 0), b3, voffB); PG8_STAGE(PG8_SB(1, 1), b3 + hstep, voffB); PG8_STAGE(PG8_SA(1, 0), a3, voffA);
;             PG8_WAIT_V(8); PG8_WAIT_L(0); PG8_BAR; PG8_MMA(1, 0, At, B0); PG8_MMA(1, 1, At, B1); PG8_BAR; PG8_SCHED;
	s_add_i32 s66, s66, s15
	v_lshl_add_u64 v[204:205], v[204:205], 0, s[24:25]
	s_mov_b32 m0, s66
	ds_read_b128 v[162:165], v254 offset:49152
	ds_read_b128 v[166:169], v254 offset:50176
	ds_read_b128 v[170:173], v254 offset:51200
	ds_read_b128 v[174:177], v254 offset:52224
	ds_read_b128 v[178:181], v254 offset:53248
	ds_read_b128 v[182:185], v254 offset:54272
	ds_read_b128 v[186:189], v254 offset:55296
	ds_read_b128 v[190:193], v254 offset:56320
	global_load_lds_dwordx4 v[204:205], off
	v_lshl_add_u64 v[204:205], v[208:209], 0, s[24:25]
	s_add_i32 m0, s66, 0x2000
	s_add_i32 s66, s77, s15
	global_load_lds_dwordx4 v[204:205], off
	v_lshl_add_u64 v[204:205], v[210:211], 0, s[24:25]
	s_mov_b32 m0, s66
	s_nop 0
	global_load_lds_dwordx4 v[204:205], off
	v_lshl_add_u64 v[204:205], v[212:213], 0, s[24:25]
	s_add_i32 m0, s66, 0x2000
	s_nop 0
	global_load_lds_dwordx4 v[204:205], off
	v_lshl_add_u64 v[204:205], v[214:215], 0, s[24:25]
	s_mov_b32 m0, s43
	s_nop 0
	global_load_lds_dwordx4 v[204:205], off
	v_lshl_add_u64 v[204:205], v[216:217], 0, s[24:25]
	s_mov_b32 m0, s44
	s_nop 0
	global_load_lds_dwordx4 v[204:205], off
	s_waitcnt vmcnt(8)
	s_waitcnt lgkmcnt(0)
	s_barrier
	s_setprio 1
	s_waitcnt lgkmcnt(0)
	v_mfma_f32_16x16x32_bf16 v[62:65], v[114:117], v[162:165], v[62:65]
	v_mfma_f32_16x16x32_bf16 v[58:61], v[126:129], v[162:165], v[58:61]
	v_mfma_f32_16x16x32_bf16 v[46:49], v[114:117], v[170:173], v[46:49]
	v_mfma_f32_16x16x32_bf16 v[42:45], v[126:129], v[170:173], v[42:45]
	v_mfma_f32_16x16x32_bf16 v[30:33], v[114:117], v[178:181], v[30:33]
	v_mfma_f32_16x16x32_bf16 v[26:29], v[126:129], v[178:181], v[26:29]
	v_mfma_f32_16x16x32_bf16 v[14:17], v[114:117], v[186:189], v[14:17]
	v_mfma_f32_16x16x32_bf16 v[10:13], v[126:129], v[186:189], v[10:13]
	v_mfma_f32_16x16x32_bf16 v[62:65], v[122:125], v[166:169], v[62:65]
	v_mfma_f32_16x16x32_bf16 v[58:61], v[130:133], v[166:169], v[58:61]
	v_mfma_f32_16x16x32_bf16 v[46:49], v[122:125], v[174:177], v[46:49]
	v_mfma_f32_16x16x32_bf16 v[42:45], v[130:133], v[174:177], v[42:45]
	v_mfma_f32_16x16x32_bf16 v[30:33], v[122:125], v[182:185], v[30:33]
	v_mfma_f32_16x16x32_bf16 v[26:29], v[130:133], v[182:185], v[26:29]
	v_mfma_f32_16x16x32_bf16 v[14:17], v[122:125], v[190:193], v[14:17]
	v_mfma_f32_16x16x32_bf16 v[10:13], v[130:133], v[190:193], v[10:13]
	s_setprio 0
	s_setprio 1
	v_mfma_f32_16x16x32_bf16 v[54:57], v[138:141], v[162:165], v[54:57]
	v_mfma_f32_16x16x32_bf16 v[50:53], v[146:149], v[162:165], v[50:53]
	v_mfma_f32_16x16x32_bf16 v[38:41], v[138:141], v[170:173], v[38:41]
	v_mfma_f32_16x16x32_bf16 v[34:37], v[146:149], v[170:173], v[34:37]
	v_mfma_f32_16x16x32_bf16 v[22:25], v[138:141], v[178:181], v[22:25]
	v_mfma_f32_16x16x32_bf16 v[18:21], v[146:149], v[178:181], v[18:21]
	v_mfma_f32_16x16x32_bf16 v[6:9], v[138:141], v[186:189], v[6:9]
	v_mfma_f32_16x16x32_bf16 v[2:5], v[146:149], v[186:189], v[2:5]
	v_mfma_f32_16x16x32_bf16 v[54:57], v[142:145], v[166:169], v[54:57]
	v_mfma_f32_16x16x32_bf16 v[50:53], v[158:161], v[166:169], v[50:53]
	v_mfma_f32_16x16x32_bf16 v[38:41], v[142:145], v[174:177], v[38:41]
	v_mfma_f32_16x16x32_bf16 v[34:37], v[158:161], v[174:177], v[34:37]
	v_mfma_f32_16x16x32_bf16 v[22:25], v[142:145], v[182:185], v[22:25]
	v_mfma_f32_16x16x32_bf16 v[18:21], v[158:161], v[182:185], v[18:21]
	v_mfma_f32_16x16x32_bf16 v[6:9], v[142:145], v[190:193], v[6:9]
	v_mfma_f32_16x16x32_bf16 v[2:5], v[158:161], v[190:193], v[2:5]
	s_setprio 0
	s_add_u32 s86, s86, 0x100
	s_addc_u32 s87, s87, 0
	s_add_u32 s64, s64, 0x100
	s_addc_u32 s65, s65, 0
	s_cmp_ge_u32 s67, s42
	s_mov_b32 s66, s67
	s_barrier
	s_cbranch_scc0 .LBB0_320
	s_and_b64 vcc, exec, s[82:83]
	s_cbranch_vccz .LBB0_323
	s_barrier

; #define PG8_STAGE(bufoff, gbase, voff) do { _Pragma("unroll") for (int _i = 0; _i < 2; ++_i) \
;         __builtin_amdgcn_global_load_lds((const unsigned*)((const char*)(gbase) + (voff)[_i]), (PG8_LAS unsigned*)(lds + (bufoff) + ldsw + _i * 8192), 16, 0, 0); } while (0)
; #define PG8_LDA(dst, b, h) do { _Pragma("unroll") for (int m = 0; m < 4; ++m) _Pragma("unroll") for (int k = 0; k < 2; ++k) dst[m][k] = *(const PG8_LAS bf16x8*)(lds + PG8_SA(b, h) + aoff + m * 2048 + k * 1024); } while (0)
; #define PG8_LDB(dst, b, h) do { _Pragma("unroll") for (int n = 0; n < 2; ++n) _Pragma("unroll") for (int k = 0; k < 2; ++k) dst[n][k] = *(const PG8_LAS bf16x8*)(lds + PG8_SB(b, h) + boff + n * 2048 + k * 1024); } while (0)
; #define PG8_MMA(ai, bj, At, Bt) do { __builtin_amdgcn_s_setprio(1); _Pragma("unroll") for (int m = 0; m < 4; ++m) _Pragma("unroll") for (int n = 0; n < 2; ++n) _Pragma("unroll") for (int k = 0; k < 2; ++k) \
;         acc[ai][bj][m][n] = __builtin_amdgcn_mfma_f32_16x16x32_bf16(Bt[n][k], At[m][k], acc[ai][bj][m][n], 0, 0, 0); __builtin_amdgcn_s_setprio(0); } while (0)
; #define PG8_WAIT_V(n) asm volatile("s_waitcnt vmcnt(" #n ")" ::: "memory")
; #define PG8_WAIT_L(n) asm volatile("s_waitcnt lgkmcnt(" #n ")" ::: "memory")
; template <class Epi, class Sched, bool ALIGN_EPI = false, bool SP2 = false>
; __device__ __forceinline__ void gemm_phase(PG8_LAS unsigned char* lds, const Gemm g, const Sched& S, const Epi& E) {
;     ...
;             const bool last = (t == nt - 2);
;             const char* a1 = cA + (size_t)(t + 1) * kstep;
;             const char* a2 = last ? nA : cA + (size_t)(t + 2) * kstep; const char* b2 = last ? nB : cB + (size_t)(t + 2) * kstep;
;             const char* a3 = a2 + kstep; const char* b3 = b2 + kstep;
;             if (last && has_next) S.a_ready(nxt);
;             if constexpr (SP2) {
;             PG8_LDB(B0, 0, 0); PG8_LDB(B1, 0, 1); PG8_SCHED; PG8_LDA(At, 0, 0); PG8_STAGE(PG8_SA(1, 1), a1 + hstep, voffA);
;             PG8_WAIT_V(8); PG8_WAIT_L(0); PG8_BAR; PG8_MMA(0, 0, At, B0); PG8_MMA(0, 1, At, B1); PG8_BAR; PG8_SCHED;
;             PG8_LDA(At, 0, 1); PG8_STAGE(PG8_SB(0, 0), b2, voffB); PG8_STAGE(PG8_SB(0, 1), b2 + hstep, voffB); PG8_STAGE(PG8_SA(0, 0), a2, voffA);
;             PG8_WAIT_V(8); PG8_WAIT_L(0); PG8_BAR; PG8_MMA(1, 0, At, B0); PG8_MMA(1, 1, At, B1); PG8_BAR; PG8_SCHED;
.LBB0_468:
	s_add_i32 s97, 0, 0x10000
	v_add_u32_e32 v140, s97, v143
	ds_read_b128 v[146:149], v140
	ds_read_b128 v[150:153], v140 offset:1024
	ds_read_b128 v[154:157], v140 offset:2048
	ds_read_b128 v[158:161], v140 offset:3072
	s_add_u32 s82, s80, 0xfffc0080
	s_addc_u32 s83, s81, -1
	s_cmp_eq_u32 s96, 12
	s_cselect_b32 s85, s75, s83
	s_cselect_b32 s84, s92, s82
	s_cselect_b32 s83, s73, s95
	s_cselect_b32 s82, s93, s94
	s_add_i32 vcc_lo, 0, 0x14000
	v_add_u32_e32 v140, vcc_lo, v143
	ds_read_b128 v[162:165], v140
	ds_read_b128 v[166:169], v140 offset:1024
	ds_read_b128 v[170:173], v140 offset:2048
	ds_read_b128 v[174:177], v140 offset:3072
	v_lshl_add_u64 v[140:141], s[80:81], 0, v[136:137]
	s_add_i32 m0, s49, 0xc000
	ds_read_b128 v[178:181], v145
	ds_read_b128 v[182:185], v145 offset:1024
	ds_read_b128 v[186:189], v145 offset:2048
	ds_read_b128 v[190:193], v145 offset:3072
	ds_read_b128 v[194:197], v145 offset:4096
	ds_read_b128 v[198:201], v145 offset:5120
	ds_read_b128 v[202:205], v145 offset:6144
	ds_read_b128 v[212:215], v145 offset:7168
	global_load_lds_dwordx4 v[140:141], off
	v_lshl_add_u64 v[140:141], s[80:81], 0, v[138:139]
	s_add_i32 m0, s49, 0xe000
	s_nop 0
	global_load_lds_dwordx4 v[140:141], off
	s_waitcnt vmcnt(8)
	s_waitcnt lgkmcnt(0)
	s_barrier
	s_setprio 1
	s_waitcnt lgkmcnt(0)
	v_mfma_f32_16x16x32_bf16 v[126:129], v[146:149], v[178:181], v[126:129]
	v_mfma_f32_16x16x32_bf16 v[122:125], v[154:157], v[178:181], v[122:125]
	v_mfma_f32_16x16x32_bf16 v[118:121], v[146:149], v[186:189], v[118:121]
	v_mfma_f32_16x16x32_bf16 v[110:113], v[154:157], v[186:189], v[110:113]
	v_mfma_f32_16x16x32_bf16 v[102:105], v[146:149], v[194:197], v[102:105]
	v_mfma_f32_16x16x32_bf16 v[94:97], v[154:157], v[194:197], v[94:97]
	v_mfma_f32_16x16x32_bf16 v[86:89], v[146:149], v[202:205], v[86:89]
	v_mfma_f32_16x16x32_bf16 v[78:81], v[154:157], v[202:205], v[78:81]
	v_mfma_f32_16x16x32_bf16 v[126:129], v[150:153], v[182:185], v[126:129]
	v_mfma_f32_16x16x32_bf16 v[122:125], v[158:161], v[182:185], v[122:125]
	v_mfma_f32_16x16x32_bf16 v[118:121], v[150:153], v[190:193], v[118:121]
	v_mfma_f32_16x16x32_bf16 v[110:113], v[158:161], v[190:193], v[110:113]
	v_mfma_f32_16x16x32_bf16 v[102:105], v[150:153], v[198:201], v[102:105]
	v_mfma_f32_16x16x32_bf16 v[94:97], v[158:161], v[198:201], v[94:97]
	v_mfma_f32_16x16x32_bf16 v[86:89], v[150:153], v[212:215], v[86:89]
	v_mfma_f32_16x16x32_bf16 v[78:81], v[158:161], v[212:215], v[78:81]
	s_setprio 0
	s_setprio 1
	v_mfma_f32_16x16x32_bf16 v[114:117], v[162:165], v[178:181], v[114:117]
	v_mfma_f32_16x16x32_bf16 v[106:109], v[170:173], v[178:181], v[106:109]
	v_mfma_f32_16x16x32_bf16 v[98:101], v[162:165], v[186:189], v[98:101]
	v_mfma_f32_16x16x32_bf16 v[90:93], v[170:173], v[186:189], v[90:93]
	v_mfma_f32_16x16x32_bf16 v[82:85], v[162:165], v[194:197], v[82:85]
	v_mfma_f32_16x16x32_bf16 v[74:77], v[170:173], v[194:197], v[74:77]
	v_mfma_f32_16x16x32_bf16 v[70:73], v[162:165], v[202:205], v[70:73]
	v_mfma_f32_16x16x32_bf16 v[66:69], v[170:173], v[202:205], v[66:69]
	v_mfma_f32_16x16x32_bf16 v[114:117], v[166:169], v[182:185], v[114:117]
	v_mfma_f32_16x16x32_bf16 v[106:109], v[174:177], v[182:185], v[106:109]
	v_mfma_f32_16x16x32_bf16 v[98:101], v[166:169], v[190:193], v[98:101]
	v_mfma_f32_16x16x32_bf16 v[90:93], v[174:177], v[190:193], v[90:93]
	v_mfma_f32_16x16x32_bf16 v[82:85], v[166:169], v[198:201], v[82:85]
	v_mfma_f32_16x16x32_bf16 v[74:77], v[174:177], v[198:201], v[74:77]
	v_mfma_f32_16x16x32_bf16 v[70:73], v[166:169], v[212:215], v[70:73]
	v_mfma_f32_16x16x32_bf16 v[66:69], v[174:177], v[212:215], v[66:69]
	s_setprio 0
	s_barrier
	s_add_i32 s97, s97, s47
	v_lshl_add_u64 v[140:141], s[82:83], 0, v[0:1]
	s_mov_b32 m0, s97
	ds_read_b128 v[178:181], v145 offset:16384
	ds_read_b128 v[182:185], v145 offset:17408
	ds_read_b128 v[186:189], v145 offset:18432
	ds_read_b128 v[190:193], v145 offset:19456
	ds_read_b128 v[194:197], v145 offset:20480
	ds_read_b128 v[198:201], v145 offset:21504
	ds_read_b128 v[202:205], v145 offset:22528
	ds_read_b128 v[212:215], v145 offset:23552
	global_load_lds_dwordx4 v[140:141], off
	s_add_i32 m0, s97, 0x2000
	s_add_u32 s98, s82, 0x40000
	v_lshl_add_u64 v[208:209], s[82:83], 0, v[130:131]
	s_addc_u32 s99, s83, 0
	s_add_i32 s97, vcc_lo, s47
	global_load_lds_dwordx4 v[208:209], off
	v_lshl_add_u64 v[210:211], s[98:99], 0, v[0:1]
	s_mov_b32 m0, s97
	v_lshl_add_u64 v[216:217], s[84:85], 0, v[132:133]
	global_load_lds_dwordx4 v[210:211], off
	v_lshl_add_u64 v[210:211], s[98:99], 0, v[130:131]
	s_add_i32 m0, s97, 0x2000
	s_nop 0
	global_load_lds_dwordx4 v[210:211], off
	v_lshl_add_u64 v[210:211], s[84:85], 0, v[134:135]
	s_mov_b32 m0, s49
	s_nop 0
	global_load_lds_dwordx4 v[210:211], off
	s_mov_b32 m0, s54
	s_nop 0
	global_load_lds_dwordx4 v[216:217], off
	s_waitcnt vmcnt(8)
	s_waitcnt lgkmcnt(0)
	s_barrier
; #define PG8_STAGE(bufoff, gbase, voff) do { _Pragma("unroll") for (int _i = 0; _i < 2; ++_i) \
;         __builtin_amdgcn_global_load_lds((const unsigned*)((const char*)(gbase) + (voff)[_i]), (PG8_LAS unsigned*)(lds + (bufoff) + ldsw + _i * 8192), 16, 0, 0); } while (0)
; #define PG8_LDA(dst, b, h) do { _Pragma("unroll") for (int m = 0; m < 4; ++m) _Pragma("unroll") for (int k = 0; k < 2; ++k) dst[m][k] = *(const PG8_LAS bf16x8*)(lds + PG8_SA(b, h) + aoff + m * 2048 + k * 1024); } while (0)
; #define PG8_LDB(dst, b, h) do { _Pragma("unroll") for (int n = 0; n < 2; ++n) _Pragma("unroll") for (int k = 0; k < 2; ++k) dst[n][k] = *(const PG8_LAS bf16x8*)(lds + PG8_SB(b, h) + boff + n * 2048 + k * 1024); } while (0)
; #define PG8_MMA(ai, bj, At, Bt) do { __builtin_amdgcn_s_setprio(1); _Pragma("unroll") for (int m = 0; m < 4; ++m) _Pragma("unroll") for (int n = 0; n < 2; ++n) _Pragma("unroll") for (int k = 0; k < 2; ++k) \
;         acc[ai][bj][m][n] = __builtin_amdgcn_mfma_f32_16x16x32_bf16(Bt[n][k], At[m][k], acc[ai][bj][m][n], 0, 0, 0); __builtin_amdgcn_s_setprio(0); } while (0)
; #define PG8_WAIT_V(n) asm volatile("s_waitcnt vmcnt(" #n ")" ::: "memory")
; #define PG8_WAIT_L(n) asm volatile("s_waitcnt lgkmcnt(" #n ")" ::: "memory")
; #define PG8_BAR __builtin_amdgcn_s_barrier()
; #define PG8_SCHED __builtin_amdgcn_sched_barrier(0)
; template <class Epi, class Sched, bool ALIGN_EPI = false, bool SP2 = false>
; __device__ __forceinline__ void gemm_phase(PG8_LAS unsigned char* lds, const Gemm g, const Sched& S, const Epi& E) {
;     ...
;             PG8_WAIT_V(8); PG8_WAIT_L(0); PG8_BAR; PG8_MMA(1, 0, At, B0); PG8_MMA(1, 1, At, B1); PG8_BAR; PG8_SCHED;
;             PG8_LDB(B0, 1, 0); PG8_LDB(B1, 1, 1); PG8_SCHED; PG8_LDA(At, 1, 0); PG8_STAGE(PG8_SA(0, 1), a2 + hstep, voffA);
;             PG8_WAIT_V(8); PG8_WAIT_L(0); PG8_BAR; PG8_MMA(0, 0, At, B0); PG8_MMA(0, 1, At, B1); PG8_BAR; PG8_SCHED;
	s_setprio 1
	s_waitcnt lgkmcnt(0)
	v_mfma_f32_16x16x32_bf16 v[62:65], v[146:149], v[178:181], v[62:65]
	v_mfma_f32_16x16x32_bf16 v[58:61], v[154:157], v[178:181], v[58:61]
	v_mfma_f32_16x16x32_bf16 v[54:57], v[146:149], v[186:189], v[54:57]
	v_mfma_f32_16x16x32_bf16 v[46:49], v[154:157], v[186:189], v[46:49]
	v_mfma_f32_16x16x32_bf16 v[38:41], v[146:149], v[194:197], v[38:41]
	v_mfma_f32_16x16x32_bf16 v[30:33], v[154:157], v[194:197], v[30:33]
	v_mfma_f32_16x16x32_bf16 v[22:25], v[146:149], v[202:205], v[22:25]
	v_mfma_f32_16x16x32_bf16 v[14:17], v[154:157], v[202:205], v[14:17]
	v_mfma_f32_16x16x32_bf16 v[62:65], v[150:153], v[182:185], v[62:65]
	v_mfma_f32_16x16x32_bf16 v[58:61], v[158:161], v[182:185], v[58:61]
	v_mfma_f32_16x16x32_bf16 v[54:57], v[150:153], v[190:193], v[54:57]
	v_mfma_f32_16x16x32_bf16 v[46:49], v[158:161], v[190:193], v[46:49]
	v_mfma_f32_16x16x32_bf16 v[38:41], v[150:153], v[198:201], v[38:41]
	v_mfma_f32_16x16x32_bf16 v[30:33], v[158:161], v[198:201], v[30:33]
	v_mfma_f32_16x16x32_bf16 v[22:25], v[150:153], v[212:215], v[22:25]
	v_mfma_f32_16x16x32_bf16 v[14:17], v[158:161], v[212:215], v[14:17]
	s_setprio 0
	s_setprio 1
	v_mfma_f32_16x16x32_bf16 v[50:53], v[162:165], v[178:181], v[50:53]
	v_mfma_f32_16x16x32_bf16 v[42:45], v[170:173], v[178:181], v[42:45]
	v_mfma_f32_16x16x32_bf16 v[34:37], v[162:165], v[186:189], v[34:37]
	v_mfma_f32_16x16x32_bf16 v[26:29], v[170:173], v[186:189], v[26:29]
	v_mfma_f32_16x16x32_bf16 v[18:21], v[162:165], v[194:197], v[18:21]
	v_mfma_f32_16x16x32_bf16 v[10:13], v[170:173], v[194:197], v[10:13]
	v_mfma_f32_16x16x32_bf16 v[6:9], v[162:165], v[202:205], v[6:9]
	v_mfma_f32_16x16x32_bf16 v[2:5], v[170:173], v[202:205], v[2:5]
	v_mfma_f32_16x16x32_bf16 v[50:53], v[166:169], v[182:185], v[50:53]
	v_mfma_f32_16x16x32_bf16 v[42:45], v[174:177], v[182:185], v[42:45]
	v_mfma_f32_16x16x32_bf16 v[34:37], v[166:169], v[190:193], v[34:37]
	v_mfma_f32_16x16x32_bf16 v[26:29], v[174:177], v[190:193], v[26:29]
	v_mfma_f32_16x16x32_bf16 v[18:21], v[166:169], v[198:201], v[18:21]
	v_mfma_f32_16x16x32_bf16 v[10:13], v[174:177], v[198:201], v[10:13]
	v_mfma_f32_16x16x32_bf16 v[6:9], v[166:169], v[212:215], v[6:9]
	v_mfma_f32_16x16x32_bf16 v[2:5], v[174:177], v[212:215], v[2:5]
	s_setprio 0
	s_barrier
	s_add_i32 s97, 0, 0x18000
	s_add_i32 s98, 0, 0x1c000
	v_add_u32_e32 v158, s97, v143
	v_add_u32_e32 v174, s98, v143
	ds_read_b128 v[146:149], v158
	ds_read_b128 v[150:153], v158 offset:1024
	ds_read_b128 v[154:157], v158 offset:2048
	ds_read_b128 v[158:161], v158 offset:3072
	ds_read_b128 v[162:165], v174
	ds_read_b128 v[166:169], v174 offset:1024
	ds_read_b128 v[170:173], v174 offset:2048
	ds_read_b128 v[174:177], v174 offset:3072
	s_add_u32 s84, s84, 0x40000
	s_addc_u32 s85, s85, 0
	s_mov_b32 m0, s55
	v_lshl_add_u64 v[218:219], s[84:85], 0, v[134:135]
	ds_read_b128 v[178:181], v145 offset:32768
	ds_read_b128 v[182:185], v145 offset:33792
	ds_read_b128 v[186:189], v145 offset:34816
	ds_read_b128 v[190:193], v145 offset:35840
	ds_read_b128 v[194:197], v145 offset:36864
	ds_read_b128 v[198:201], v145 offset:37888
	ds_read_b128 v[202:205], v145 offset:38912
	ds_read_b128 v[212:215], v145 offset:39936
	global_load_lds_dwordx4 v[218:219], off
	v_lshl_add_u64 v[218:219], s[84:85], 0, v[132:133]
	s_mov_b32 m0, s66
	s_nop 0
	global_load_lds_dwordx4 v[218:219], off
	s_waitcnt vmcnt(8)
	s_waitcnt lgkmcnt(0)
	s_barrier
	s_setprio 1
	s_waitcnt lgkmcnt(0)
	v_mfma_f32_16x16x32_bf16 v[126:129], v[146:149], v[178:181], v[126:129]
	v_mfma_f32_16x16x32_bf16 v[122:125], v[154:157], v[178:181], v[122:125]
	v_mfma_f32_16x16x32_bf16 v[118:121], v[146:149], v[186:189], v[118:121]
	v_mfma_f32_16x16x32_bf16 v[110:113], v[154:157], v[186:189], v[110:113]
	v_mfma_f32_16x16x32_bf16 v[102:105], v[146:149], v[194:197], v[102:105]
	v_mfma_f32_16x16x32_bf16 v[94:97], v[154:157], v[194:197], v[94:97]
	v_mfma_f32_16x16x32_bf16 v[86:89], v[146:149], v[202:205], v[86:89]
	v_mfma_f32_16x16x32_bf16 v[78:81], v[154:157], v[202:205], v[78:81]
	v_mfma_f32_16x16x32_bf16 v[126:129], v[150:153], v[182:185], v[126:129]
	v_mfma_f32_16x16x32_bf16 v[122:125], v[158:161], v[182:185], v[122:125]
	v_mfma_f32_16x16x32_bf16 v[118:121], v[150:153], v[190:193], v[118:121]
	v_mfma_f32_16x16x32_bf16 v[110:113], v[158:161], v[190:193], v[110:113]
	v_mfma_f32_16x16x32_bf16 v[102:105], v[150:153], v[198:201], v[102:105]
	v_mfma_f32_16x16x32_bf16 v[94:97], v[158:161], v[198:201], v[94:97]
	v_mfma_f32_16x16x32_bf16 v[86:89], v[150:153], v[212:215], v[86:89]
	v_mfma_f32_16x16x32_bf16 v[78:81], v[158:161], v[212:215], v[78:81]
	s_setprio 0
	s_setprio 1
	v_mfma_f32_16x16x32_bf16 v[114:117], v[162:165], v[178:181], v[114:117]
	v_mfma_f32_16x16x32_bf16 v[106:109], v[170:173], v[178:181], v[106:109]
	v_mfma_f32_16x16x32_bf16 v[98:101], v[162:165], v[186:189], v[98:101]
	v_mfma_f32_16x16x32_bf16 v[90:93], v[170:173], v[186:189], v[90:93]
	v_mfma_f32_16x16x32_bf16 v[82:85], v[162:165], v[194:197], v[82:85]
	v_mfma_f32_16x16x32_bf16 v[74:77], v[170:173], v[194:197], v[74:77]
	v_mfma_f32_16x16x32_bf16 v[70:73], v[162:165], v[202:205], v[70:73]
	v_mfma_f32_16x16x32_bf16 v[66:69], v[170:173], v[202:205], v[66:69]
	v_mfma_f32_16x16x32_bf16 v[114:117], v[166:169], v[182:185], v[114:117]
	v_mfma_f32_16x16x32_bf16 v[106:109], v[174:177], v[182:185], v[106:109]
	v_mfma_f32_16x16x32_bf16 v[98:101], v[166:169], v[190:193], v[98:101]
	v_mfma_f32_16x16x32_bf16 v[90:93], v[174:177], v[190:193], v[90:93]
	v_mfma_f32_16x16x32_bf16 v[82:85], v[166:169], v[198:201], v[82:85]
	v_mfma_f32_16x16x32_bf16 v[74:77], v[174:177], v[198:201], v[74:77]
	v_mfma_f32_16x16x32_bf16 v[70:73], v[166:169], v[212:215], v[70:73]
	v_mfma_f32_16x16x32_bf16 v[66:69], v[174:177], v[212:215], v[66:69]
	s_setprio 0
	s_barrier
; #define PG8_STAGE(bufoff, gbase, voff) do { _Pragma("unroll") for (int _i = 0; _i < 2; ++_i) \
;         __builtin_amdgcn_global_load_lds((const unsigned*)((const char*)(gbase) + (voff)[_i]), (PG8_LAS unsigned*)(lds + (bufoff) + ldsw + _i * 8192), 16, 0, 0); } while (0)
; #define PG8_LDA(dst, b, h) do { _Pragma("unroll") for (int m = 0; m < 4; ++m) _Pragma("unroll") for (int k = 0; k < 2; ++k) dst[m][k] = *(const PG8_LAS bf16x8*)(lds + PG8_SA(b, h) + aoff + m * 2048 + k * 1024); } while (0)
; #define PG8_MMA(ai, bj, At, Bt) do { __builtin_amdgcn_s_setprio(1); _Pragma("unroll") for (int m = 0; m < 4; ++m) _Pragma("unroll") for (int n = 0; n < 2; ++n) _Pragma("unroll") for (int k = 0; k < 2; ++k) \
;         acc[ai][bj][m][n] = __builtin_amdgcn_mfma_f32_16x16x32_bf16(Bt[n][k], At[m][k], acc[ai][bj][m][n], 0, 0, 0); __builtin_amdgcn_s_setprio(0); } while (0)
; #define PG8_WAIT_V(n) asm volatile("s_waitcnt vmcnt(" #n ")" ::: "memory")
; #define PG8_WAIT_L(n) asm volatile("s_waitcnt lgkmcnt(" #n ")" ::: "memory")
; #define PG8_BAR __builtin_amdgcn_s_barrier()
; #define PG8_SCHED __builtin_amdgcn_sched_barrier(0)
; template <class Epi, class Sched, bool ALIGN_EPI = false, bool SP2 = false>
; __device__ __forceinline__ void gemm_phase(PG8_LAS unsigned char* lds, const Gemm g, const Sched& S, const Epi& E) {
;     ...
;             PG8_LDA(At, 1, 1); PG8_STAGE(PG8_SB(1, 0), b3, voffB); PG8_STAGE(PG8_SB(1, 1), b3 + hstep, voffB); PG8_STAGE(PG8_SA(1, 0), a3, voffA);
;             PG8_WAIT_V(8); PG8_WAIT_L(0); PG8_BAR; PG8_MMA(1, 0, At, B0); PG8_MMA(1, 1, At, B1); PG8_BAR; PG8_SCHED;
	s_add_i32 s84, s97, s47
	v_lshl_add_u64 v[140:141], v[140:141], 0, s[24:25]
	s_mov_b32 m0, s84
	ds_read_b128 v[178:181], v145 offset:49152
	ds_read_b128 v[182:185], v145 offset:50176
	ds_read_b128 v[186:189], v145 offset:51200
	ds_read_b128 v[190:193], v145 offset:52224
	ds_read_b128 v[194:197], v145 offset:53248
	ds_read_b128 v[198:201], v145 offset:54272
	ds_read_b128 v[202:205], v145 offset:55296
	ds_read_b128 v[212:215], v145 offset:56320
	global_load_lds_dwordx4 v[140:141], off
	s_add_i32 m0, s84, 0x2000
	s_add_u32 s82, s82, 0x40080
	v_lshl_add_u64 v[140:141], v[208:209], 0, s[24:25]
	s_addc_u32 s83, s83, 0
	s_add_i32 s84, s98, s47
	global_load_lds_dwordx4 v[140:141], off
	v_lshl_add_u64 v[140:141], s[82:83], 0, v[0:1]
	s_mov_b32 m0, s84
	s_nop 0
	global_load_lds_dwordx4 v[140:141], off
	v_lshl_add_u64 v[140:141], s[82:83], 0, v[130:131]
	s_add_i32 m0, s84, 0x2000
	s_nop 0
	global_load_lds_dwordx4 v[140:141], off
	v_lshl_add_u64 v[140:141], v[210:211], 0, s[24:25]
	s_mov_b32 m0, s67
	s_nop 0
	global_load_lds_dwordx4 v[140:141], off
	v_lshl_add_u64 v[140:141], v[216:217], 0, s[24:25]
	s_mov_b32 m0, s88
	s_nop 0
	global_load_lds_dwordx4 v[140:141], off
	s_waitcnt vmcnt(8)
	s_waitcnt lgkmcnt(0)
	s_barrier
	s_setprio 1
	s_waitcnt lgkmcnt(0)
	v_mfma_f32_16x16x32_bf16 v[62:65], v[146:149], v[178:181], v[62:65]
	v_mfma_f32_16x16x32_bf16 v[58:61], v[154:157], v[178:181], v[58:61]
	v_mfma_f32_16x16x32_bf16 v[54:57], v[146:149], v[186:189], v[54:57]
	v_mfma_f32_16x16x32_bf16 v[46:49], v[154:157], v[186:189], v[46:49]
	v_mfma_f32_16x16x32_bf16 v[38:41], v[146:149], v[194:197], v[38:41]
	v_mfma_f32_16x16x32_bf16 v[30:33], v[154:157], v[194:197], v[30:33]
	v_mfma_f32_16x16x32_bf16 v[22:25], v[146:149], v[202:205], v[22:25]
	v_mfma_f32_16x16x32_bf16 v[14:17], v[154:157], v[202:205], v[14:17]
	v_mfma_f32_16x16x32_bf16 v[62:65], v[150:153], v[182:185], v[62:65]
	v_mfma_f32_16x16x32_bf16 v[58:61], v[158:161], v[182:185], v[58:61]
	v_mfma_f32_16x16x32_bf16 v[54:57], v[150:153], v[190:193], v[54:57]
	v_mfma_f32_16x16x32_bf16 v[46:49], v[158:161], v[190:193], v[46:49]
	v_mfma_f32_16x16x32_bf16 v[38:41], v[150:153], v[198:201], v[38:41]
	v_mfma_f32_16x16x32_bf16 v[30:33], v[158:161], v[198:201], v[30:33]
	v_mfma_f32_16x16x32_bf16 v[22:25], v[150:153], v[212:215], v[22:25]
	v_mfma_f32_16x16x32_bf16 v[14:17], v[158:161], v[212:215], v[14:17]
	s_setprio 0
	s_setprio 1
	v_mfma_f32_16x16x32_bf16 v[50:53], v[162:165], v[178:181], v[50:53]
	v_mfma_f32_16x16x32_bf16 v[42:45], v[170:173], v[178:181], v[42:45]
	v_mfma_f32_16x16x32_bf16 v[34:37], v[162:165], v[186:189], v[34:37]
	v_mfma_f32_16x16x32_bf16 v[26:29], v[170:173], v[186:189], v[26:29]
	v_mfma_f32_16x16x32_bf16 v[18:21], v[162:165], v[194:197], v[18:21]
	v_mfma_f32_16x16x32_bf16 v[10:13], v[170:173], v[194:197], v[10:13]
	v_mfma_f32_16x16x32_bf16 v[6:9], v[162:165], v[202:205], v[6:9]
	v_mfma_f32_16x16x32_bf16 v[2:5], v[170:173], v[202:205], v[2:5]
	v_mfma_f32_16x16x32_bf16 v[50:53], v[166:169], v[182:185], v[50:53]
	v_mfma_f32_16x16x32_bf16 v[42:45], v[174:177], v[182:185], v[42:45]
	v_mfma_f32_16x16x32_bf16 v[34:37], v[166:169], v[190:193], v[34:37]
	v_mfma_f32_16x16x32_bf16 v[26:29], v[174:177], v[190:193], v[26:29]
	v_mfma_f32_16x16x32_bf16 v[18:21], v[166:169], v[198:201], v[18:21]
	v_mfma_f32_16x16x32_bf16 v[10:13], v[174:177], v[198:201], v[10:13]
	v_mfma_f32_16x16x32_bf16 v[6:9], v[166:169], v[212:215], v[6:9]
	v_mfma_f32_16x16x32_bf16 v[2:5], v[174:177], v[212:215], v[2:5]
	s_setprio 0
	s_add_i32 s96, s96, 2
	s_add_u32 s80, s80, 0x100
	s_addc_u32 s81, s81, 0
	s_add_u32 s94, s94, 0x100
	s_addc_u32 s95, s95, 0
	s_cmp_gt_u32 s96, 13
	s_barrier
	s_cbranch_scc0 .LBB0_468
	s_and_b64 vcc, exec, s[70:71]
	s_cbranch_vccz .LBB0_471
	s_barrier

; #define PG8_STAGE(bufoff, gbase, voff) do { _Pragma("unroll") for (int _i = 0; _i < 2; ++_i) \
;         __builtin_amdgcn_global_load_lds((const unsigned*)((const char*)(gbase) + (voff)[_i]), (PG8_LAS unsigned*)(lds + (bufoff) + ldsw + _i * 8192), 16, 0, 0); } while (0)
; #define PG8_LDA(dst, b, h) do { _Pragma("unroll") for (int m = 0; m < 4; ++m) _Pragma("unroll") for (int k = 0; k < 2; ++k) dst[m][k] = *(const PG8_LAS bf16x8*)(lds + PG8_SA(b, h) + aoff + m * 2048 + k * 1024); } while (0)
; #define PG8_LDB(dst, b, h) do { _Pragma("unroll") for (int n = 0; n < 2; ++n) _Pragma("unroll") for (int k = 0; k < 2; ++k) dst[n][k] = *(const PG8_LAS bf16x8*)(lds + PG8_SB(b, h) + boff + n * 2048 + k * 1024); } while (0)
; #define PG8_MMA(ai, bj, At, Bt) do { __builtin_amdgcn_s_setprio(1); _Pragma("unroll") for (int m = 0; m < 4; ++m) _Pragma("unroll") for (int n = 0; n < 2; ++n) _Pragma("unroll") for (int k = 0; k < 2; ++k) \
;         acc[ai][bj][m][n] = __builtin_amdgcn_mfma_f32_16x16x32_bf16(Bt[n][k], At[m][k], acc[ai][bj][m][n], 0, 0, 0); __builtin_amdgcn_s_setprio(0); } while (0)
; #define PG8_WAIT_V(n) asm volatile("s_waitcnt vmcnt(" #n ")" ::: "memory")
; #define PG8_WAIT_L(n) asm volatile("s_waitcnt lgkmcnt(" #n ")" ::: "memory")
; template <class Epi, class Sched, bool ALIGN_EPI = false, bool SP2 = false>
; __device__ __forceinline__ void gemm_phase(PG8_LAS unsigned char* lds, const Gemm g, const Sched& S, const Epi& E) {
;     ...
;             const bool last = (t == nt - 2);
;             const char* a1 = cA + (size_t)(t + 1) * kstep;
;             const char* a2 = last ? nA : cA + (size_t)(t + 2) * kstep; const char* b2 = last ? nB : cB + (size_t)(t + 2) * kstep;
;             const char* a3 = a2 + kstep; const char* b3 = b2 + kstep;
;             if (last && has_next) S.a_ready(nxt);
;             if constexpr (SP2) {
;             PG8_LDB(B0, 0, 0); PG8_LDB(B1, 0, 1); PG8_SCHED; PG8_LDA(At, 0, 0); PG8_STAGE(PG8_SA(1, 1), a1 + hstep, voffA);
;             PG8_WAIT_V(8); PG8_WAIT_L(0); PG8_BAR; PG8_MMA(0, 0, At, B0); PG8_MMA(0, 1, At, B1); PG8_BAR; PG8_SCHED;
;             PG8_LDA(At, 0, 1); PG8_STAGE(PG8_SB(0, 0), b2, voffB); PG8_STAGE(PG8_SB(0, 1), b2 + hstep, voffB); PG8_STAGE(PG8_SA(0, 0), a2, voffA);
;             PG8_WAIT_V(8); PG8_WAIT_L(0); PG8_BAR; PG8_MMA(1, 0, At, B0); PG8_MMA(1, 1, At, B1); PG8_BAR; PG8_SCHED;
.LBB0_509:
	s_add_i32 s89, 0, 0x10000
	v_add_u32_e32 v0, s89, v149
	ds_read_b128 v[142:145], v0
	ds_read_b128 v[154:157], v0 offset:1024
	ds_read_b128 v[158:161], v0 offset:2048
	ds_read_b128 v[162:165], v0 offset:3072
	s_add_u32 s78, s76, 0xfffc0080
	s_addc_u32 s79, s77, -1
	s_cmp_eq_u32 s88, 12
	s_cselect_b32 s81, s69, s79
	s_cselect_b32 s80, s75, s78
	s_cselect_b32 s79, s67, s85
	s_cselect_b32 s78, s83, s84
	s_add_i32 s92, 0, 0x14000
	v_add_u32_e32 v0, s92, v149
	ds_read_b128 v[166:169], v0
	ds_read_b128 v[170:173], v0 offset:1024
	ds_read_b128 v[174:177], v0 offset:2048
	ds_read_b128 v[178:181], v0 offset:3072
	v_lshl_add_u64 v[208:209], s[76:77], 0, v[138:139]
	s_add_i32 m0, s7, 0xc000
	ds_read_b128 v[182:185], v152
	ds_read_b128 v[186:189], v152 offset:1024
	ds_read_b128 v[190:193], v152 offset:2048
	ds_read_b128 v[194:197], v152 offset:3072
	ds_read_b128 v[198:201], v152 offset:4096
	ds_read_b128 v[202:205], v152 offset:5120
	ds_read_b128 v[212:215], v152 offset:6144
	ds_read_b128 v[216:219], v152 offset:7168
	global_load_lds_dwordx4 v[208:209], off
	v_lshl_add_u64 v[208:209], s[76:77], 0, v[140:141]
	s_add_i32 m0, s7, 0xe000
	s_nop 0
	global_load_lds_dwordx4 v[208:209], off
	s_waitcnt vmcnt(8)
	s_waitcnt lgkmcnt(0)
	s_barrier
	s_setprio 1
	s_waitcnt lgkmcnt(0)
	v_mfma_f32_16x16x32_bf16 v[126:129], v[142:145], v[182:185], v[126:129]
	v_mfma_f32_16x16x32_bf16 v[122:125], v[158:161], v[182:185], v[122:125]
	v_mfma_f32_16x16x32_bf16 v[110:113], v[142:145], v[190:193], v[110:113]
	v_mfma_f32_16x16x32_bf16 v[106:109], v[158:161], v[190:193], v[106:109]
	v_mfma_f32_16x16x32_bf16 v[94:97], v[142:145], v[198:201], v[94:97]
	v_mfma_f32_16x16x32_bf16 v[90:93], v[158:161], v[198:201], v[90:93]
	v_mfma_f32_16x16x32_bf16 v[78:81], v[142:145], v[212:215], v[78:81]
	v_mfma_f32_16x16x32_bf16 v[74:77], v[158:161], v[212:215], v[74:77]
	v_mfma_f32_16x16x32_bf16 v[126:129], v[154:157], v[186:189], v[126:129]
	v_mfma_f32_16x16x32_bf16 v[122:125], v[162:165], v[186:189], v[122:125]
	v_mfma_f32_16x16x32_bf16 v[110:113], v[154:157], v[194:197], v[110:113]
	v_mfma_f32_16x16x32_bf16 v[106:109], v[162:165], v[194:197], v[106:109]
	v_mfma_f32_16x16x32_bf16 v[94:97], v[154:157], v[202:205], v[94:97]
	v_mfma_f32_16x16x32_bf16 v[90:93], v[162:165], v[202:205], v[90:93]
	v_mfma_f32_16x16x32_bf16 v[78:81], v[154:157], v[216:219], v[78:81]
	v_mfma_f32_16x16x32_bf16 v[74:77], v[162:165], v[216:219], v[74:77]
	s_setprio 0
	s_setprio 1
	v_mfma_f32_16x16x32_bf16 v[118:121], v[166:169], v[182:185], v[118:121]
	v_mfma_f32_16x16x32_bf16 v[114:117], v[174:177], v[182:185], v[114:117]
	v_mfma_f32_16x16x32_bf16 v[102:105], v[166:169], v[190:193], v[102:105]
	v_mfma_f32_16x16x32_bf16 v[98:101], v[174:177], v[190:193], v[98:101]
	v_mfma_f32_16x16x32_bf16 v[86:89], v[166:169], v[198:201], v[86:89]
	v_mfma_f32_16x16x32_bf16 v[82:85], v[174:177], v[198:201], v[82:85]
	v_mfma_f32_16x16x32_bf16 v[70:73], v[166:169], v[212:215], v[70:73]
	v_mfma_f32_16x16x32_bf16 v[66:69], v[174:177], v[212:215], v[66:69]
	v_mfma_f32_16x16x32_bf16 v[118:121], v[170:173], v[186:189], v[118:121]
	v_mfma_f32_16x16x32_bf16 v[114:117], v[178:181], v[186:189], v[114:117]
	v_mfma_f32_16x16x32_bf16 v[102:105], v[170:173], v[194:197], v[102:105]
	v_mfma_f32_16x16x32_bf16 v[98:101], v[178:181], v[194:197], v[98:101]
	v_mfma_f32_16x16x32_bf16 v[86:89], v[170:173], v[202:205], v[86:89]
	v_mfma_f32_16x16x32_bf16 v[82:85], v[178:181], v[202:205], v[82:85]
	v_mfma_f32_16x16x32_bf16 v[70:73], v[170:173], v[216:219], v[70:73]
	v_mfma_f32_16x16x32_bf16 v[66:69], v[178:181], v[216:219], v[66:69]
	s_setprio 0
	s_barrier
	s_add_i32 s89, s89, s26
	v_lshl_add_u64 v[208:209], s[78:79], 0, v[132:133]
	s_mov_b32 m0, s89
	ds_read_b128 v[182:185], v152 offset:16384
	ds_read_b128 v[186:189], v152 offset:17408
	ds_read_b128 v[190:193], v152 offset:18432
	ds_read_b128 v[194:197], v152 offset:19456
	ds_read_b128 v[198:201], v152 offset:20480
	ds_read_b128 v[202:205], v152 offset:21504
	ds_read_b128 v[212:215], v152 offset:22528
	ds_read_b128 v[216:219], v152 offset:23552
	global_load_lds_dwordx4 v[208:209], off
	s_add_i32 m0, s89, 0x2000
	s_add_u32 s90, s78, 0x40000
	v_lshl_add_u64 v[210:211], s[78:79], 0, v[136:137]
	s_addc_u32 s91, s79, 0
	s_add_i32 s89, s92, s26
	global_load_lds_dwordx4 v[210:211], off
	v_lshl_add_u64 v[220:221], s[90:91], 0, v[132:133]
	s_mov_b32 m0, s89
	v_lshl_add_u64 v[222:223], s[80:81], 0, v[134:135]
	global_load_lds_dwordx4 v[220:221], off
	v_lshl_add_u64 v[220:221], s[90:91], 0, v[136:137]
	s_add_i32 m0, s89, 0x2000
	s_nop 0
	global_load_lds_dwordx4 v[220:221], off
	v_lshl_add_u64 v[220:221], s[80:81], 0, v[130:131]
	s_mov_b32 m0, s7
	s_nop 0
	global_load_lds_dwordx4 v[220:221], off
	s_mov_b32 m0, s27
	s_nop 0
	global_load_lds_dwordx4 v[222:223], off
	s_waitcnt vmcnt(8)
	s_waitcnt lgkmcnt(0)
	s_barrier
; #define PG8_STAGE(bufoff, gbase, voff) do { _Pragma("unroll") for (int _i = 0; _i < 2; ++_i) \
;         __builtin_amdgcn_global_load_lds((const unsigned*)((const char*)(gbase) + (voff)[_i]), (PG8_LAS unsigned*)(lds + (bufoff) + ldsw + _i * 8192), 16, 0, 0); } while (0)
; #define PG8_LDA(dst, b, h) do { _Pragma("unroll") for (int m = 0; m < 4; ++m) _Pragma("unroll") for (int k = 0; k < 2; ++k) dst[m][k] = *(const PG8_LAS bf16x8*)(lds + PG8_SA(b, h) + aoff + m * 2048 + k * 1024); } while (0)
; #define PG8_LDB(dst, b, h) do { _Pragma("unroll") for (int n = 0; n < 2; ++n) _Pragma("unroll") for (int k = 0; k < 2; ++k) dst[n][k] = *(const PG8_LAS bf16x8*)(lds + PG8_SB(b, h) + boff + n * 2048 + k * 1024); } while (0)
; #define PG8_MMA(ai, bj, At, Bt) do { __builtin_amdgcn_s_setprio(1); _Pragma("unroll") for (int m = 0; m < 4; ++m) _Pragma("unroll") for (int n = 0; n < 2; ++n) _Pragma("unroll") for (int k = 0; k < 2; ++k) \
;         acc[ai][bj][m][n] = __builtin_amdgcn_mfma_f32_16x16x32_bf16(Bt[n][k], At[m][k], acc[ai][bj][m][n], 0, 0, 0); __builtin_amdgcn_s_setprio(0); } while (0)
; #define PG8_WAIT_V(n) asm volatile("s_waitcnt vmcnt(" #n ")" ::: "memory")
; #define PG8_WAIT_L(n) asm volatile("s_waitcnt lgkmcnt(" #n ")" ::: "memory")
; #define PG8_BAR __builtin_amdgcn_s_barrier()
; #define PG8_SCHED __builtin_amdgcn_sched_barrier(0)
; template <class Epi, class Sched, bool ALIGN_EPI = false, bool SP2 = false>
; __device__ __forceinline__ void gemm_phase(PG8_LAS unsigned char* lds, const Gemm g, const Sched& S, const Epi& E) {
;     ...
;             PG8_WAIT_V(8); PG8_WAIT_L(0); PG8_BAR; PG8_MMA(1, 0, At, B0); PG8_MMA(1, 1, At, B1); PG8_BAR; PG8_SCHED;
;             PG8_LDB(B0, 1, 0); PG8_LDB(B1, 1, 1); PG8_SCHED; PG8_LDA(At, 1, 0); PG8_STAGE(PG8_SA(0, 1), a2 + hstep, voffA);
;             PG8_WAIT_V(8); PG8_WAIT_L(0); PG8_BAR; PG8_MMA(0, 0, At, B0); PG8_MMA(0, 1, At, B1); PG8_BAR; PG8_SCHED;
	s_setprio 1
	s_waitcnt lgkmcnt(0)
	v_mfma_f32_16x16x32_bf16 v[62:65], v[142:145], v[182:185], v[62:65]
	v_mfma_f32_16x16x32_bf16 v[58:61], v[158:161], v[182:185], v[58:61]
	v_mfma_f32_16x16x32_bf16 v[46:49], v[142:145], v[190:193], v[46:49]
	v_mfma_f32_16x16x32_bf16 v[42:45], v[158:161], v[190:193], v[42:45]
	v_mfma_f32_16x16x32_bf16 v[30:33], v[142:145], v[198:201], v[30:33]
	v_mfma_f32_16x16x32_bf16 v[26:29], v[158:161], v[198:201], v[26:29]
	v_mfma_f32_16x16x32_bf16 v[14:17], v[142:145], v[212:215], v[14:17]
	v_mfma_f32_16x16x32_bf16 v[10:13], v[158:161], v[212:215], v[10:13]
	v_mfma_f32_16x16x32_bf16 v[62:65], v[154:157], v[186:189], v[62:65]
	v_mfma_f32_16x16x32_bf16 v[58:61], v[162:165], v[186:189], v[58:61]
	v_mfma_f32_16x16x32_bf16 v[46:49], v[154:157], v[194:197], v[46:49]
	v_mfma_f32_16x16x32_bf16 v[42:45], v[162:165], v[194:197], v[42:45]
	v_mfma_f32_16x16x32_bf16 v[30:33], v[154:157], v[202:205], v[30:33]
	v_mfma_f32_16x16x32_bf16 v[26:29], v[162:165], v[202:205], v[26:29]
	v_mfma_f32_16x16x32_bf16 v[14:17], v[154:157], v[216:219], v[14:17]
	v_mfma_f32_16x16x32_bf16 v[10:13], v[162:165], v[216:219], v[10:13]
	s_setprio 0
	s_setprio 1
	v_mfma_f32_16x16x32_bf16 v[54:57], v[166:169], v[182:185], v[54:57]
	v_mfma_f32_16x16x32_bf16 v[50:53], v[174:177], v[182:185], v[50:53]
	v_mfma_f32_16x16x32_bf16 v[38:41], v[166:169], v[190:193], v[38:41]
	v_mfma_f32_16x16x32_bf16 v[34:37], v[174:177], v[190:193], v[34:37]
	v_mfma_f32_16x16x32_bf16 v[22:25], v[166:169], v[198:201], v[22:25]
	v_mfma_f32_16x16x32_bf16 v[18:21], v[174:177], v[198:201], v[18:21]
	v_mfma_f32_16x16x32_bf16 v[6:9], v[166:169], v[212:215], v[6:9]
	v_mfma_f32_16x16x32_bf16 v[2:5], v[174:177], v[212:215], v[2:5]
	v_mfma_f32_16x16x32_bf16 v[54:57], v[170:173], v[186:189], v[54:57]
	v_mfma_f32_16x16x32_bf16 v[50:53], v[178:181], v[186:189], v[50:53]
	v_mfma_f32_16x16x32_bf16 v[38:41], v[170:173], v[194:197], v[38:41]
	v_mfma_f32_16x16x32_bf16 v[34:37], v[178:181], v[194:197], v[34:37]
	v_mfma_f32_16x16x32_bf16 v[22:25], v[170:173], v[202:205], v[22:25]
	v_mfma_f32_16x16x32_bf16 v[18:21], v[178:181], v[202:205], v[18:21]
	v_mfma_f32_16x16x32_bf16 v[6:9], v[170:173], v[216:219], v[6:9]
	v_mfma_f32_16x16x32_bf16 v[2:5], v[178:181], v[216:219], v[2:5]
	s_setprio 0
	s_barrier
	s_add_i32 s89, 0, 0x18000
	v_add_u32_e32 v0, s89, v149
	s_add_i32 s90, 0, 0x1c000
	ds_read_b128 v[142:145], v0
	ds_read_b128 v[154:157], v0 offset:1024
	ds_read_b128 v[158:161], v0 offset:2048
	ds_read_b128 v[162:165], v0 offset:3072
	v_add_u32_e32 v0, s90, v149
	ds_read_b128 v[166:169], v0
	ds_read_b128 v[170:173], v0 offset:1024
	ds_read_b128 v[174:177], v0 offset:2048
	ds_read_b128 v[178:181], v0 offset:3072
	s_add_u32 s80, s80, 0x40000
	s_addc_u32 s81, s81, 0
	s_mov_b32 m0, s28
	v_lshl_add_u64 v[224:225], s[80:81], 0, v[130:131]
	ds_read_b128 v[182:185], v152 offset:32768
	ds_read_b128 v[186:189], v152 offset:33792
	ds_read_b128 v[190:193], v152 offset:34816
	ds_read_b128 v[194:197], v152 offset:35840
	ds_read_b128 v[198:201], v152 offset:36864
	ds_read_b128 v[202:205], v152 offset:37888
	ds_read_b128 v[212:215], v152 offset:38912
	ds_read_b128 v[216:219], v152 offset:39936
	global_load_lds_dwordx4 v[224:225], off
	v_lshl_add_u64 v[224:225], s[80:81], 0, v[134:135]
	s_mov_b32 m0, s29
	s_nop 0
	global_load_lds_dwordx4 v[224:225], off
	s_waitcnt vmcnt(8)
	s_waitcnt lgkmcnt(0)
	s_barrier
	s_setprio 1
	s_waitcnt lgkmcnt(0)
	v_mfma_f32_16x16x32_bf16 v[126:129], v[142:145], v[182:185], v[126:129]
	v_mfma_f32_16x16x32_bf16 v[122:125], v[158:161], v[182:185], v[122:125]
	v_mfma_f32_16x16x32_bf16 v[110:113], v[142:145], v[190:193], v[110:113]
	v_mfma_f32_16x16x32_bf16 v[106:109], v[158:161], v[190:193], v[106:109]
	v_mfma_f32_16x16x32_bf16 v[94:97], v[142:145], v[198:201], v[94:97]
	v_mfma_f32_16x16x32_bf16 v[90:93], v[158:161], v[198:201], v[90:93]
	v_mfma_f32_16x16x32_bf16 v[78:81], v[142:145], v[212:215], v[78:81]
	v_mfma_f32_16x16x32_bf16 v[74:77], v[158:161], v[212:215], v[74:77]
	v_mfma_f32_16x16x32_bf16 v[126:129], v[154:157], v[186:189], v[126:129]
	v_mfma_f32_16x16x32_bf16 v[122:125], v[162:165], v[186:189], v[122:125]
	v_mfma_f32_16x16x32_bf16 v[110:113], v[154:157], v[194:197], v[110:113]
	v_mfma_f32_16x16x32_bf16 v[106:109], v[162:165], v[194:197], v[106:109]
	v_mfma_f32_16x16x32_bf16 v[94:97], v[154:157], v[202:205], v[94:97]
	v_mfma_f32_16x16x32_bf16 v[90:93], v[162:165], v[202:205], v[90:93]
	v_mfma_f32_16x16x32_bf16 v[78:81], v[154:157], v[216:219], v[78:81]
	v_mfma_f32_16x16x32_bf16 v[74:77], v[162:165], v[216:219], v[74:77]
	s_setprio 0
	s_setprio 1
	v_mfma_f32_16x16x32_bf16 v[118:121], v[166:169], v[182:185], v[118:121]
	v_mfma_f32_16x16x32_bf16 v[114:117], v[174:177], v[182:185], v[114:117]
	v_mfma_f32_16x16x32_bf16 v[102:105], v[166:169], v[190:193], v[102:105]
	v_mfma_f32_16x16x32_bf16 v[98:101], v[174:177], v[190:193], v[98:101]
	v_mfma_f32_16x16x32_bf16 v[86:89], v[166:169], v[198:201], v[86:89]
	v_mfma_f32_16x16x32_bf16 v[82:85], v[174:177], v[198:201], v[82:85]
	v_mfma_f32_16x16x32_bf16 v[70:73], v[166:169], v[212:215], v[70:73]
	v_mfma_f32_16x16x32_bf16 v[66:69], v[174:177], v[212:215], v[66:69]
	v_mfma_f32_16x16x32_bf16 v[118:121], v[170:173], v[186:189], v[118:121]
	v_mfma_f32_16x16x32_bf16 v[114:117], v[178:181], v[186:189], v[114:117]
	v_mfma_f32_16x16x32_bf16 v[102:105], v[170:173], v[194:197], v[102:105]
	v_mfma_f32_16x16x32_bf16 v[98:101], v[178:181], v[194:197], v[98:101]
	v_mfma_f32_16x16x32_bf16 v[86:89], v[170:173], v[202:205], v[86:89]
	v_mfma_f32_16x16x32_bf16 v[82:85], v[178:181], v[202:205], v[82:85]
	v_mfma_f32_16x16x32_bf16 v[70:73], v[170:173], v[216:219], v[70:73]
	v_mfma_f32_16x16x32_bf16 v[66:69], v[178:181], v[216:219], v[66:69]
	s_setprio 0
	s_barrier
; #define PG8_STAGE(bufoff, gbase, voff) do { _Pragma("unroll") for (int _i = 0; _i < 2; ++_i) \
;         __builtin_amdgcn_global_load_lds((const unsigned*)((const char*)(gbase) + (voff)[_i]), (PG8_LAS unsigned*)(lds + (bufoff) + ldsw + _i * 8192), 16, 0, 0); } while (0)
; #define PG8_LDA(dst, b, h) do { _Pragma("unroll") for (int m = 0; m < 4; ++m) _Pragma("unroll") for (int k = 0; k < 2; ++k) dst[m][k] = *(const PG8_LAS bf16x8*)(lds + PG8_SA(b, h) + aoff + m * 2048 + k * 1024); } while (0)
; #define PG8_MMA(ai, bj, At, Bt) do { __builtin_amdgcn_s_setprio(1); _Pragma("unroll") for (int m = 0; m < 4; ++m) _Pragma("unroll") for (int n = 0; n < 2; ++n) _Pragma("unroll") for (int k = 0; k < 2; ++k) \
;         acc[ai][bj][m][n] = __builtin_amdgcn_mfma_f32_16x16x32_bf16(Bt[n][k], At[m][k], acc[ai][bj][m][n], 0, 0, 0); __builtin_amdgcn_s_setprio(0); } while (0)
; #define PG8_WAIT_V(n) asm volatile("s_waitcnt vmcnt(" #n ")" ::: "memory")
; #define PG8_WAIT_L(n) asm volatile("s_waitcnt lgkmcnt(" #n ")" ::: "memory")
; #define PG8_BAR __builtin_amdgcn_s_barrier()
; #define PG8_SCHED __builtin_amdgcn_sched_barrier(0)
; template <class Epi, class Sched, bool ALIGN_EPI = false, bool SP2 = false>
; __device__ __forceinline__ void gemm_phase(PG8_LAS unsigned char* lds, const Gemm g, const Sched& S, const Epi& E) {
;     ...
;             PG8_LDA(At, 1, 1); PG8_STAGE(PG8_SB(1, 0), b3, voffB); PG8_STAGE(PG8_SB(1, 1), b3 + hstep, voffB); PG8_STAGE(PG8_SA(1, 0), a3, voffA);
;             PG8_WAIT_V(8); PG8_WAIT_L(0); PG8_BAR; PG8_MMA(1, 0, At, B0); PG8_MMA(1, 1, At, B1); PG8_BAR; PG8_SCHED;
;     ...
;         if constexpr (ALIGN_EPI) { if (wr == 0) PG8_BAR; }
	s_add_i32 s80, s89, s26
	v_lshl_add_u64 v[208:209], v[208:209], 0, s[24:25]
	s_mov_b32 m0, s80
	ds_read_b128 v[182:185], v152 offset:49152
	ds_read_b128 v[186:189], v152 offset:50176
	ds_read_b128 v[190:193], v152 offset:51200
	ds_read_b128 v[194:197], v152 offset:52224
	ds_read_b128 v[198:201], v152 offset:53248
	ds_read_b128 v[202:205], v152 offset:54272
	ds_read_b128 v[212:215], v152 offset:55296
	ds_read_b128 v[216:219], v152 offset:56320
	global_load_lds_dwordx4 v[208:209], off
	s_add_i32 m0, s80, 0x2000
	s_add_u32 s78, s78, 0x40080
	v_lshl_add_u64 v[208:209], v[210:211], 0, s[24:25]
	s_addc_u32 s79, s79, 0
	s_add_i32 s80, s90, s26
	global_load_lds_dwordx4 v[208:209], off
	v_lshl_add_u64 v[208:209], s[78:79], 0, v[132:133]
	s_mov_b32 m0, s80
	s_nop 0
	global_load_lds_dwordx4 v[208:209], off
	v_lshl_add_u64 v[208:209], s[78:79], 0, v[136:137]
	s_add_i32 m0, s80, 0x2000
	s_nop 0
	global_load_lds_dwordx4 v[208:209], off
	v_lshl_add_u64 v[208:209], v[220:221], 0, s[24:25]
	s_mov_b32 m0, s43
	s_nop 0
	global_load_lds_dwordx4 v[208:209], off
	v_lshl_add_u64 v[208:209], v[222:223], 0, s[24:25]
	s_mov_b32 m0, s44
	s_nop 0
	global_load_lds_dwordx4 v[208:209], off
	s_waitcnt vmcnt(8)
	s_waitcnt lgkmcnt(0)
	s_barrier
	s_setprio 1
	s_waitcnt lgkmcnt(0)
	v_mfma_f32_16x16x32_bf16 v[62:65], v[142:145], v[182:185], v[62:65]
	v_mfma_f32_16x16x32_bf16 v[58:61], v[158:161], v[182:185], v[58:61]
	v_mfma_f32_16x16x32_bf16 v[46:49], v[142:145], v[190:193], v[46:49]
	v_mfma_f32_16x16x32_bf16 v[42:45], v[158:161], v[190:193], v[42:45]
	v_mfma_f32_16x16x32_bf16 v[30:33], v[142:145], v[198:201], v[30:33]
	v_mfma_f32_16x16x32_bf16 v[26:29], v[158:161], v[198:201], v[26:29]
	v_mfma_f32_16x16x32_bf16 v[14:17], v[142:145], v[212:215], v[14:17]
	v_mfma_f32_16x16x32_bf16 v[10:13], v[158:161], v[212:215], v[10:13]
	v_mfma_f32_16x16x32_bf16 v[62:65], v[154:157], v[186:189], v[62:65]
	v_mfma_f32_16x16x32_bf16 v[58:61], v[162:165], v[186:189], v[58:61]
	v_mfma_f32_16x16x32_bf16 v[46:49], v[154:157], v[194:197], v[46:49]
	v_mfma_f32_16x16x32_bf16 v[42:45], v[162:165], v[194:197], v[42:45]
	v_mfma_f32_16x16x32_bf16 v[30:33], v[154:157], v[202:205], v[30:33]
	v_mfma_f32_16x16x32_bf16 v[26:29], v[162:165], v[202:205], v[26:29]
	v_mfma_f32_16x16x32_bf16 v[14:17], v[154:157], v[216:219], v[14:17]
	v_mfma_f32_16x16x32_bf16 v[10:13], v[162:165], v[216:219], v[10:13]
	s_setprio 0
	s_setprio 1
	v_mfma_f32_16x16x32_bf16 v[54:57], v[166:169], v[182:185], v[54:57]
	v_mfma_f32_16x16x32_bf16 v[50:53], v[174:177], v[182:185], v[50:53]
	v_mfma_f32_16x16x32_bf16 v[38:41], v[166:169], v[190:193], v[38:41]
	v_mfma_f32_16x16x32_bf16 v[34:37], v[174:177], v[190:193], v[34:37]
	v_mfma_f32_16x16x32_bf16 v[22:25], v[166:169], v[198:201], v[22:25]
	v_mfma_f32_16x16x32_bf16 v[18:21], v[174:177], v[198:201], v[18:21]
	v_mfma_f32_16x16x32_bf16 v[6:9], v[166:169], v[212:215], v[6:9]
	v_mfma_f32_16x16x32_bf16 v[2:5], v[174:177], v[212:215], v[2:5]
	v_mfma_f32_16x16x32_bf16 v[54:57], v[170:173], v[186:189], v[54:57]
	v_mfma_f32_16x16x32_bf16 v[50:53], v[178:181], v[186:189], v[50:53]
	v_mfma_f32_16x16x32_bf16 v[38:41], v[170:173], v[194:197], v[38:41]
	v_mfma_f32_16x16x32_bf16 v[34:37], v[178:181], v[194:197], v[34:37]
	v_mfma_f32_16x16x32_bf16 v[22:25], v[170:173], v[202:205], v[22:25]
	v_mfma_f32_16x16x32_bf16 v[18:21], v[178:181], v[202:205], v[18:21]
	v_mfma_f32_16x16x32_bf16 v[6:9], v[170:173], v[216:219], v[6:9]
	v_mfma_f32_16x16x32_bf16 v[2:5], v[178:181], v[216:219], v[2:5]
	s_setprio 0
	s_add_i32 s88, s88, 2
	s_add_u32 s76, s76, 0x100
	s_addc_u32 s77, s77, 0
	s_add_u32 s84, s84, 0x100
	s_addc_u32 s85, s85, 0
	s_cmp_gt_u32 s88, 13
	s_barrier
	s_cbranch_scc0 .LBB0_509
	s_and_b64 vcc, exec, s[64:65]
	s_cbranch_vccz .LBB0_546
	s_barrier
	v_lshl_add_u32 v142, s6, 8, v148
	s_cmp_ge_i32 s74, s42
	s_mov_b64 s[76:77], -1
	s_cbranch_scc1 .LBB0_547
